# nt cache hint on residual-stream f32 loads and in-place x stores in the three residual epilogues (on top of rout deep prefetch)
# baseline (speedup 1.0000x reference)
; __device__ __forceinline__ unsigned cvt_pk_bf16(float lo, float hi) { unsigned r; asm volatile("v_cvt_pk_bf16_f32 %0, %1, %2" : "=v"(r) : "v"(lo), "v"(hi)); return r; }
; #define PG8_WAIT_V(n) asm volatile("s_waitcnt vmcnt(" #n ")" ::: "memory")
; #define PG8_BAR __builtin_amdgcn_s_barrier()
;     __device__ __forceinline__ void fused(f32x4 (&acc)[2][2][4][2], const Unit& u, int wr, int wc, int fr, int fq, PG8_LAS unsigned char* lds, int wid, int lane) const {
;     ...
; #pragma unroll
;         for (int ai = 0; ai < 2; ++ai)
; #pragma unroll
;             for (int m = 0; m < 4; ++m) { const int rl = ai * HALF + wr * 64 + m * 16 + fr; const size_t off = (size_t)(u.pm * BM + rl) * ldc + col0; float q = 0.f;
; #pragma unroll
;                 for (int bj = 0; bj < 2; ++bj) { const u32x4 hb = *(const u32x4*)(xb + off + bj * HALF);
;                     const f32x4 b0 = (f32x4){__uint_as_float(hb.x << 16), __uint_as_float(hb.x & 0xffff0000u), __uint_as_float(hb.y << 16), __uint_as_float(hb.y & 0xffff0000u)};
;                     const f32x4 b1 = (f32x4){__uint_as_float(hb.z << 16), __uint_as_float(hb.z & 0xffff0000u), __uint_as_float(hb.w << 16), __uint_as_float(hb.w & 0xffff0000u)};
;                     const f32x4 v0 = b0 + acc[ai][bj][m][0], v1 = b1 + acc[ai][bj][m][1];
;                     u32x4 w; w.x = cvt_pk_bf16(v0[0], v0[1]); w.y = cvt_pk_bf16(v0[2], v0[3]); w.z = cvt_pk_bf16(v1[0], v1[1]); w.w = cvt_pk_bf16(v1[2], v1[3]);
;                     *(u32x4*)(xb + off + bj * HALF) = w;
;                     q += (v0[0] * v0[0] + v0[1] * v0[1]) + (v0[2] * v0[2] + v0[3] * v0[3]) + (v1[0] * v1[0] + v1[1] * v1[1]) + (v1[2] * v1[2] + v1[3] * v1[3]); }
;                 q += __shfl_xor(q, 16); q += __shfl_xor(q, 32);
;                 if (fq == 0) P[rl * 4 + wc] = q; }
; template <class Epi, class Sched, bool ALIGN_EPI = false, bool SP2 = false>
; __device__ __forceinline__ void gemm_phase(PG8_LAS unsigned char* lds, const Gemm g, const Sched& S, const Epi& E) {
;     ...
;     PG8_WAIT_V(0);
;     if constexpr (!ALIGN_EPI) { if (wr == 0) PG8_BAR; }
;     PG8_BAR;
;     if constexpr (Epi::AFTER_DRAIN) { E.fused(acc, cur, wr, wc, fr, fq, lds, wid, lane); S.done(cur); }
.LBB0_205:
	s_lshl_b32 s2, s43, 5
	s_lshl_b32 s3, s0, 8
	s_or_b32 s2, s3, s2
	s_lshl_b32 s3, s44, 8
	v_lshrrev_b32_e32 v180, 1, v149
	v_and_or_b32 v180, v180, 24, s2
	v_add_u32_e32 v181, s3, v148
	v_lshlrev_b32_e32 v181, 12, v181
	v_lshl_add_u32 v181, v180, 1, v181
	v_readlane_b32 s2, v252, 36
	v_readlane_b32 s3, v252, 37
	s_nop 4
	global_load_dwordx4 v[152:155], v181, s[2:3] nt
	global_load_dwordx4 v[156:159], v181, s[2:3] offset:256 nt
	v_add_u32_e32 v181, 0x10000, v181
	global_load_dwordx4 v[160:163], v181, s[2:3] nt
	global_load_dwordx4 v[164:167], v181, s[2:3] offset:256 nt
	v_add_u32_e32 v181, 0x10000, v181
	global_load_dwordx4 v[168:171], v181, s[2:3] nt
	global_load_dwordx4 v[172:175], v181, s[2:3] offset:256 nt
	v_add_u32_e32 v181, 0x10000, v181
	global_load_dwordx4 v[176:179], v181, s[2:3] nt
	global_load_dwordx4 v[184:187], v181, s[2:3] offset:256 nt
	v_add_u32_e32 v181, 0x50000, v181
	global_load_dwordx4 v[188:191], v181, s[2:3] nt
	global_load_dwordx4 v[192:195], v181, s[2:3] offset:256 nt
	v_add_u32_e32 v181, 0x10000, v181
	global_load_dwordx4 v[196:199], v181, s[2:3] nt
	global_load_dwordx4 v[200:203], v181, s[2:3] offset:256 nt
	v_add_u32_e32 v181, 0x10000, v181
	global_load_dwordx4 v[204:207], v181, s[2:3] nt
	global_load_dwordx4 v[224:227], v181, s[2:3] offset:256 nt
	v_add_u32_e32 v181, 0x10000, v181
	global_load_dwordx4 v[228:231], v181, s[2:3] nt
	global_load_dwordx4 v[232:235], v181, s[2:3] offset:256 nt
	s_waitcnt vmcnt(16)
	s_cmpk_gt_u32 s1, 0xff
	s_cbranch_scc1 .LBB0_207
	s_barrier
.LBB0_207:
	s_lshl_b32 s2, s43, 5
	s_lshl_b32 s3, s0, 8
	s_lshl_b32 s4, s44, 8
	v_lshrrev_b32_e32 v0, 1, v149
	s_or_b32 s2, s3, s2
	v_add_u32_e32 v136, s4, v148
	v_and_or_b32 v2, v0, 24, s2
	v_ashrrev_i32_e32 v137, 31, v136
	v_readlane_b32 s2, v252, 36
	v_lshlrev_b64 v[136:137], 12, v[136:137]
	v_readlane_b32 s3, v252, 37
	v_ashrrev_i32_e32 v3, 31, v2
	s_barrier
	v_lshl_add_u64 v[136:137], s[2:3], 0, v[136:137]
	v_lshl_add_u64 v[140:141], v[2:3], 1, v[136:137]
	v_cmp_lt_i32_e32 vcc, v219, v214
	v_and_b32_e32 v0, 63, v149
	s_lshl_b32 s2, s43, 2
	s_add_i32 s5, s2, 0
	s_waitcnt vmcnt(15)
	v_lshlrev_b32_e32 v142, 16, v152
	v_and_b32_e32 v143, 0xffff0000, v152
	v_lshlrev_b32_e32 v136, 16, v153
	v_and_b32_e32 v137, 0xffff0000, v153
	v_lshlrev_b32_e32 v144, 16, v154
	v_and_b32_e32 v145, 0xffff0000, v154
	v_lshlrev_b32_e32 v138, 16, v155
	v_and_b32_e32 v139, 0xffff0000, v155
	v_pk_add_f32 v[146:147], v[134:135], v[136:137]
	v_pk_add_f32 v[142:143], v[132:133], v[142:143]
	v_pk_add_f32 v[138:139], v[130:131], v[138:139]
	v_pk_add_f32 v[144:145], v[128:129], v[144:145]
	v_cvt_pk_bf16_f32 v130, v142, v143
	v_cvt_pk_bf16_f32 v131, v146, v147
	v_mul_f32_e32 v143, v143, v143
	v_cvt_pk_bf16_f32 v132, v144, v145
	v_cvt_pk_bf16_f32 v133, v138, v139
	v_mul_f32_e32 v147, v147, v147
	v_mul_f32_e32 v145, v145, v145
	v_mul_f32_e32 v139, v139, v139
	v_fmac_f32_e32 v143, v142, v142
	v_fmac_f32_e32 v147, v146, v146
	v_fmac_f32_e32 v145, v144, v144
	v_fmac_f32_e32 v139, v138, v138
	v_add_f32_e32 v138, v143, v147
	v_add_f32_e32 v138, v145, v138
	v_add_f32_e32 v144, v139, v138
	v_cndmask_b32_e32 v128, v213, v219, vcc
	v_lshlrev_b32_e32 v128, 2, v128
	v_cmp_lt_i32_e32 vcc, v220, v214
	global_store_dwordx4 v[140:141], v[130:133], off nt
	s_waitcnt vmcnt(15)
	v_lshlrev_b32_e32 v138, 16, v156
	v_and_b32_e32 v139, 0xffff0000, v156
	v_lshlrev_b32_e32 v134, 16, v157
	v_and_b32_e32 v135, 0xffff0000, v157
	v_lshlrev_b32_e32 v142, 16, v158
	v_and_b32_e32 v143, 0xffff0000, v158
	v_lshlrev_b32_e32 v136, 16, v159
	v_and_b32_e32 v137, 0xffff0000, v159
	v_pk_add_f32 v[126:127], v[126:127], v[134:135]
	v_pk_add_f32 v[124:125], v[124:125], v[138:139]
	v_pk_add_f32 v[134:135], v[122:123], v[136:137]
	v_pk_add_f32 v[136:137], v[120:121], v[142:143]
	v_mul_f32_e32 v120, v125, v125
	v_mul_f32_e32 v121, v127, v127
	v_mul_f32_e32 v122, v137, v137
	v_fmac_f32_e32 v120, v124, v124
	v_fmac_f32_e32 v121, v126, v126
	v_mul_f32_e32 v123, v135, v135
	v_fmac_f32_e32 v122, v136, v136
	v_add_f32_e32 v120, v120, v121
	v_fmac_f32_e32 v123, v134, v134
	v_add_f32_e32 v120, v122, v120
	v_add_f32_e32 v120, v123, v120
	v_add_f32_e32 v120, v144, v120
	ds_bpermute_b32 v121, v128, v120
	v_cndmask_b32_e32 v129, v213, v220, vcc
	v_cmp_gt_u32_e32 vcc, 16, v0
	v_cvt_pk_bf16_f32 v124, v124, v125
	v_cvt_pk_bf16_f32 v125, v126, v127
	s_waitcnt lgkmcnt(0)
	v_add_f32_e32 v121, v120, v121
	v_lshlrev_b32_e32 v120, 2, v129
	ds_bpermute_b32 v122, v120, v121
	v_cvt_pk_bf16_f32 v126, v136, v137
	v_cvt_pk_bf16_f32 v127, v134, v135
	global_store_dwordx4 v[140:141], v[124:127], off offset:256 nt
	s_and_saveexec_b64 s[2:3], vcc
	s_movk_i32 s37, 0x2000
	s_cbranch_execz .LBB0_209
	v_lshl_add_u32 v123, v148, 4, s5
	s_waitcnt lgkmcnt(0)
	v_add_f32_e32 v121, v121, v122
	ds_write_b32 v123, v121
; __device__ __forceinline__ unsigned cvt_pk_bf16(float lo, float hi) { unsigned r; asm volatile("v_cvt_pk_bf16_f32 %0, %1, %2" : "=v"(r) : "v"(lo), "v"(hi)); return r; }
;     __device__ __forceinline__ void fused(f32x4 (&acc)[2][2][4][2], const Unit& u, int wr, int wc, int fr, int fq, PG8_LAS unsigned char* lds, int wid, int lane) const {
;     ...
;         for (int ai = 0; ai < 2; ++ai)
; #pragma unroll
;             for (int m = 0; m < 4; ++m) { const int rl = ai * HALF + wr * 64 + m * 16 + fr; const size_t off = (size_t)(u.pm * BM + rl) * ldc + col0; float q = 0.f;
; #pragma unroll
;                 for (int bj = 0; bj < 2; ++bj) { const u32x4 hb = *(const u32x4*)(xb + off + bj * HALF);
;                     const f32x4 b0 = (f32x4){__uint_as_float(hb.x << 16), __uint_as_float(hb.x & 0xffff0000u), __uint_as_float(hb.y << 16), __uint_as_float(hb.y & 0xffff0000u)};
;                     const f32x4 b1 = (f32x4){__uint_as_float(hb.z << 16), __uint_as_float(hb.z & 0xffff0000u), __uint_as_float(hb.w << 16), __uint_as_float(hb.w & 0xffff0000u)};
;                     const f32x4 v0 = b0 + acc[ai][bj][m][0], v1 = b1 + acc[ai][bj][m][1];
;                     u32x4 w; w.x = cvt_pk_bf16(v0[0], v0[1]); w.y = cvt_pk_bf16(v0[2], v0[3]); w.z = cvt_pk_bf16(v1[0], v1[1]); w.w = cvt_pk_bf16(v1[2], v1[3]);
;                     *(u32x4*)(xb + off + bj * HALF) = w;
;                     q += (v0[0] * v0[0] + v0[1] * v0[1]) + (v0[2] * v0[2] + v0[3] * v0[3]) + (v1[0] * v1[0] + v1[1] * v1[1]) + (v1[2] * v1[2] + v1[3] * v1[3]); }
;                 q += __shfl_xor(q, 16); q += __shfl_xor(q, 32);
;                 if (fq == 0) P[rl * 4 + wc] = q; }
.LBB0_209:
	s_or_b64 exec, exec, s[2:3]
	v_or_b32_e32 v121, 16, v148
	s_waitcnt lgkmcnt(0)
	v_add_u32_e32 v122, s4, v121
	v_ashrrev_i32_e32 v123, 31, v122
	v_readlane_b32 s2, v252, 36
	v_lshlrev_b64 v[122:123], 12, v[122:123]
	v_readlane_b32 s3, v252, 37
	s_nop 1
	v_lshl_add_u64 v[122:123], s[2:3], 0, v[122:123]
	v_lshl_add_u64 v[126:127], v[2:3], 1, v[122:123]
	s_waitcnt vmcnt(15)
	v_lshlrev_b32_e32 v130, 16, v160
	v_and_b32_e32 v131, 0xffff0000, v160
	v_lshlrev_b32_e32 v122, 16, v161
	v_and_b32_e32 v123, 0xffff0000, v161
	v_lshlrev_b32_e32 v132, 16, v162
	v_and_b32_e32 v133, 0xffff0000, v162
	v_lshlrev_b32_e32 v124, 16, v163
	v_and_b32_e32 v125, 0xffff0000, v163
	v_pk_add_f32 v[122:123], v[118:119], v[122:123]
	v_pk_add_f32 v[130:131], v[116:117], v[130:131]
	v_pk_add_f32 v[124:125], v[114:115], v[124:125]
	v_pk_add_f32 v[132:133], v[112:113], v[132:133]
	v_cvt_pk_bf16_f32 v112, v130, v131
	v_cvt_pk_bf16_f32 v113, v122, v123
	v_mul_f32_e32 v129, v131, v131
	v_cvt_pk_bf16_f32 v114, v132, v133
	v_cvt_pk_bf16_f32 v115, v124, v125
	v_mul_f32_e32 v123, v123, v123
	v_mul_f32_e32 v131, v133, v133
	v_fmac_f32_e32 v129, v130, v130
	v_fmac_f32_e32 v123, v122, v122
	v_mul_f32_e32 v125, v125, v125
	v_fmac_f32_e32 v131, v132, v132
	v_add_f32_e32 v122, v129, v123
	v_fmac_f32_e32 v125, v124, v124
	v_add_f32_e32 v122, v131, v122
	v_add_f32_e32 v129, v125, v122
	global_store_dwordx4 v[126:127], v[112:115], off nt
	s_waitcnt vmcnt(15)
	v_lshlrev_b32_e32 v122, 16, v164
	v_and_b32_e32 v123, 0xffff0000, v164
	v_lshlrev_b32_e32 v116, 16, v165
	v_and_b32_e32 v117, 0xffff0000, v165
	v_lshlrev_b32_e32 v124, 16, v166
	v_and_b32_e32 v125, 0xffff0000, v166
	v_lshlrev_b32_e32 v118, 16, v167
	v_and_b32_e32 v119, 0xffff0000, v167
	v_pk_add_f32 v[110:111], v[110:111], v[116:117]
	v_pk_add_f32 v[108:109], v[108:109], v[122:123]
	v_pk_add_f32 v[116:117], v[106:107], v[118:119]
	v_pk_add_f32 v[118:119], v[104:105], v[124:125]
	v_mul_f32_e32 v104, v109, v109
	v_mul_f32_e32 v105, v111, v111
	v_mul_f32_e32 v106, v119, v119
	v_fmac_f32_e32 v104, v108, v108
	v_fmac_f32_e32 v105, v110, v110
	v_mul_f32_e32 v107, v117, v117
	v_fmac_f32_e32 v106, v118, v118
	v_add_f32_e32 v104, v104, v105
	v_add_f32_e32 v104, v106, v104
	v_fmac_f32_e32 v107, v116, v116
	v_add_f32_e32 v104, v107, v104
	v_add_f32_e32 v104, v129, v104
	ds_bpermute_b32 v105, v128, v104
	v_cvt_pk_bf16_f32 v106, v108, v109
	v_cvt_pk_bf16_f32 v107, v110, v111
	v_cvt_pk_bf16_f32 v108, v118, v119
	v_cvt_pk_bf16_f32 v109, v116, v117
	s_waitcnt lgkmcnt(0)
	v_add_f32_e32 v104, v104, v105
	ds_bpermute_b32 v105, v120, v104
	global_store_dwordx4 v[126:127], v[106:109], off offset:256 nt
	s_and_saveexec_b64 s[2:3], vcc
	s_cbranch_execz .LBB0_211
	v_lshl_add_u32 v106, v121, 4, s5
	s_waitcnt lgkmcnt(0)
	v_add_f32_e32 v104, v104, v105
	ds_write_b32 v106, v104
.LBB0_211:
	s_or_b64 exec, exec, s[2:3]
	v_or_b32_e32 v104, 32, v148
	v_add_u32_e32 v106, s4, v104
	v_ashrrev_i32_e32 v107, 31, v106
	v_readlane_b32 s2, v252, 36
	v_lshlrev_b64 v[106:107], 12, v[106:107]
	v_readlane_b32 s3, v252, 37
	s_nop 1
	v_lshl_add_u64 v[106:107], s[2:3], 0, v[106:107]
	v_lshl_add_u64 v[110:111], v[2:3], 1, v[106:107]
	s_waitcnt vmcnt(15)
	v_lshlrev_b32_e32 v112, 16, v168
	v_and_b32_e32 v113, 0xffff0000, v168
	v_lshlrev_b32_e32 v106, 16, v169
	v_and_b32_e32 v107, 0xffff0000, v169
	v_lshlrev_b32_e32 v114, 16, v170
	v_and_b32_e32 v115, 0xffff0000, v170
	v_lshlrev_b32_e32 v108, 16, v171
	v_and_b32_e32 v109, 0xffff0000, v171
	v_pk_add_f32 v[106:107], v[102:103], v[106:107]
	v_pk_add_f32 v[112:113], v[100:101], v[112:113]
	v_pk_add_f32 v[108:109], v[98:99], v[108:109]
	v_pk_add_f32 v[114:115], v[96:97], v[114:115]
	v_cvt_pk_bf16_f32 v96, v112, v113
	v_cvt_pk_bf16_f32 v97, v106, v107
	s_waitcnt lgkmcnt(0)
	v_mul_f32_e32 v105, v113, v113
	v_cvt_pk_bf16_f32 v98, v114, v115
	v_cvt_pk_bf16_f32 v99, v108, v109
	v_mul_f32_e32 v107, v107, v107
	v_mul_f32_e32 v113, v115, v115
	v_fmac_f32_e32 v105, v112, v112
	v_fmac_f32_e32 v107, v106, v106
	v_mul_f32_e32 v109, v109, v109
	v_fmac_f32_e32 v113, v114, v114
	v_add_f32_e32 v105, v105, v107
	v_fmac_f32_e32 v109, v108, v108
	v_add_f32_e32 v105, v113, v105
	v_add_f32_e32 v105, v109, v105
	global_store_dwordx4 v[110:111], v[96:99], off nt
	s_waitcnt vmcnt(15)
	v_lshlrev_b32_e32 v106, 16, v172
	v_and_b32_e32 v107, 0xffff0000, v172
	v_lshlrev_b32_e32 v100, 16, v173
	v_and_b32_e32 v101, 0xffff0000, v173
	v_lshlrev_b32_e32 v108, 16, v174
	v_and_b32_e32 v109, 0xffff0000, v174
	v_lshlrev_b32_e32 v102, 16, v175
	v_and_b32_e32 v103, 0xffff0000, v175
	v_pk_add_f32 v[94:95], v[94:95], v[100:101]
	v_pk_add_f32 v[92:93], v[92:93], v[106:107]
	v_pk_add_f32 v[100:101], v[90:91], v[102:103]
	v_pk_add_f32 v[102:103], v[88:89], v[108:109]
	v_mul_f32_e32 v88, v93, v93
	v_mul_f32_e32 v89, v95, v95
	v_mul_f32_e32 v90, v103, v103
	v_fmac_f32_e32 v88, v92, v92
	v_fmac_f32_e32 v89, v94, v94
	v_mul_f32_e32 v91, v101, v101
	v_fmac_f32_e32 v90, v102, v102
	v_add_f32_e32 v88, v88, v89
	v_add_f32_e32 v88, v90, v88
	v_fmac_f32_e32 v91, v100, v100
	v_add_f32_e32 v88, v91, v88
	v_add_f32_e32 v88, v105, v88
	ds_bpermute_b32 v89, v128, v88
	v_cvt_pk_bf16_f32 v90, v92, v93
	v_cvt_pk_bf16_f32 v91, v94, v95
	v_cvt_pk_bf16_f32 v92, v102, v103
	v_cvt_pk_bf16_f32 v93, v100, v101
	s_waitcnt lgkmcnt(0)
	v_add_f32_e32 v88, v88, v89
	ds_bpermute_b32 v89, v120, v88
	global_store_dwordx4 v[110:111], v[90:93], off offset:256 nt
	s_and_saveexec_b64 s[2:3], vcc
	s_cbranch_execz .LBB0_213
	v_lshl_add_u32 v90, v104, 4, s5
	s_waitcnt lgkmcnt(0)
	v_add_f32_e32 v88, v88, v89
	ds_write_b32 v90, v88
; __device__ __forceinline__ unsigned cvt_pk_bf16(float lo, float hi) { unsigned r; asm volatile("v_cvt_pk_bf16_f32 %0, %1, %2" : "=v"(r) : "v"(lo), "v"(hi)); return r; }
;     __device__ __forceinline__ void fused(f32x4 (&acc)[2][2][4][2], const Unit& u, int wr, int wc, int fr, int fq, PG8_LAS unsigned char* lds, int wid, int lane) const {
;     ...
;         for (int ai = 0; ai < 2; ++ai)
; #pragma unroll
;             for (int m = 0; m < 4; ++m) { const int rl = ai * HALF + wr * 64 + m * 16 + fr; const size_t off = (size_t)(u.pm * BM + rl) * ldc + col0; float q = 0.f;
; #pragma unroll
;                 for (int bj = 0; bj < 2; ++bj) { const u32x4 hb = *(const u32x4*)(xb + off + bj * HALF);
;                     const f32x4 b0 = (f32x4){__uint_as_float(hb.x << 16), __uint_as_float(hb.x & 0xffff0000u), __uint_as_float(hb.y << 16), __uint_as_float(hb.y & 0xffff0000u)};
;                     const f32x4 b1 = (f32x4){__uint_as_float(hb.z << 16), __uint_as_float(hb.z & 0xffff0000u), __uint_as_float(hb.w << 16), __uint_as_float(hb.w & 0xffff0000u)};
;                     const f32x4 v0 = b0 + acc[ai][bj][m][0], v1 = b1 + acc[ai][bj][m][1];
;                     u32x4 w; w.x = cvt_pk_bf16(v0[0], v0[1]); w.y = cvt_pk_bf16(v0[2], v0[3]); w.z = cvt_pk_bf16(v1[0], v1[1]); w.w = cvt_pk_bf16(v1[2], v1[3]);
;                     *(u32x4*)(xb + off + bj * HALF) = w;
;                     q += (v0[0] * v0[0] + v0[1] * v0[1]) + (v0[2] * v0[2] + v0[3] * v0[3]) + (v1[0] * v1[0] + v1[1] * v1[1]) + (v1[2] * v1[2] + v1[3] * v1[3]); }
;                 q += __shfl_xor(q, 16); q += __shfl_xor(q, 32);
;                 if (fq == 0) P[rl * 4 + wc] = q; }
.LBB0_213:
	s_or_b64 exec, exec, s[2:3]
	v_or_b32_e32 v88, 48, v148
	v_add_u32_e32 v90, s4, v88
	v_ashrrev_i32_e32 v91, 31, v90
	v_readlane_b32 s2, v252, 36
	v_lshlrev_b64 v[90:91], 12, v[90:91]
	v_readlane_b32 s3, v252, 37
	s_nop 1
	v_lshl_add_u64 v[90:91], s[2:3], 0, v[90:91]
	v_lshl_add_u64 v[94:95], v[2:3], 1, v[90:91]
	s_waitcnt vmcnt(15)
	v_lshlrev_b32_e32 v96, 16, v176
	v_and_b32_e32 v97, 0xffff0000, v176
	v_lshlrev_b32_e32 v90, 16, v177
	v_and_b32_e32 v91, 0xffff0000, v177
	v_lshlrev_b32_e32 v98, 16, v178
	v_and_b32_e32 v99, 0xffff0000, v178
	v_lshlrev_b32_e32 v92, 16, v179
	v_and_b32_e32 v93, 0xffff0000, v179
	v_pk_add_f32 v[90:91], v[86:87], v[90:91]
	v_pk_add_f32 v[96:97], v[84:85], v[96:97]
	v_pk_add_f32 v[92:93], v[82:83], v[92:93]
	v_pk_add_f32 v[98:99], v[80:81], v[98:99]
	v_cvt_pk_bf16_f32 v80, v96, v97
	v_cvt_pk_bf16_f32 v81, v90, v91
	s_waitcnt lgkmcnt(0)
	v_mul_f32_e32 v89, v97, v97
	v_cvt_pk_bf16_f32 v82, v98, v99
	v_cvt_pk_bf16_f32 v83, v92, v93
	v_mul_f32_e32 v91, v91, v91
	v_mul_f32_e32 v97, v99, v99
	v_fmac_f32_e32 v89, v96, v96
	v_fmac_f32_e32 v91, v90, v90
	v_mul_f32_e32 v93, v93, v93
	v_fmac_f32_e32 v97, v98, v98
	v_add_f32_e32 v89, v89, v91
	v_fmac_f32_e32 v93, v92, v92
	v_add_f32_e32 v89, v97, v89
	v_add_f32_e32 v89, v93, v89
	global_store_dwordx4 v[94:95], v[80:83], off nt
	s_waitcnt vmcnt(15)
	v_lshlrev_b32_e32 v90, 16, v184
	v_and_b32_e32 v91, 0xffff0000, v184
	v_lshlrev_b32_e32 v84, 16, v185
	v_and_b32_e32 v85, 0xffff0000, v185
	v_lshlrev_b32_e32 v92, 16, v186
	v_and_b32_e32 v93, 0xffff0000, v186
	v_lshlrev_b32_e32 v86, 16, v187
	v_and_b32_e32 v87, 0xffff0000, v187
	v_pk_add_f32 v[78:79], v[78:79], v[84:85]
	v_pk_add_f32 v[76:77], v[76:77], v[90:91]
	v_pk_add_f32 v[84:85], v[74:75], v[86:87]
	v_pk_add_f32 v[86:87], v[72:73], v[92:93]
	v_mul_f32_e32 v72, v77, v77
	v_mul_f32_e32 v73, v79, v79
	v_mul_f32_e32 v74, v87, v87
	v_fmac_f32_e32 v72, v76, v76
	v_fmac_f32_e32 v73, v78, v78
	v_mul_f32_e32 v75, v85, v85
	v_fmac_f32_e32 v74, v86, v86
	v_add_f32_e32 v72, v72, v73
	v_add_f32_e32 v72, v74, v72
	v_fmac_f32_e32 v75, v84, v84
	v_add_f32_e32 v72, v75, v72
	v_add_f32_e32 v72, v89, v72
	ds_bpermute_b32 v73, v128, v72
	v_cvt_pk_bf16_f32 v74, v76, v77
	v_cvt_pk_bf16_f32 v75, v78, v79
	v_cvt_pk_bf16_f32 v76, v86, v87
	v_cvt_pk_bf16_f32 v77, v84, v85
	s_waitcnt lgkmcnt(0)
	v_add_f32_e32 v72, v72, v73
	ds_bpermute_b32 v73, v120, v72
	global_store_dwordx4 v[94:95], v[74:77], off offset:256 nt
	s_and_saveexec_b64 s[2:3], vcc
	s_cbranch_execz .LBB0_215
	v_lshl_add_u32 v74, v88, 4, s5
	s_waitcnt lgkmcnt(0)
	v_add_f32_e32 v72, v72, v73
	ds_write_b32 v74, v72
.LBB0_215:
	s_or_b64 exec, exec, s[2:3]
	v_add_u32_e32 v72, 0x80, v148
	v_add_u32_e32 v74, s4, v72
	v_ashrrev_i32_e32 v75, 31, v74
	v_readlane_b32 s2, v252, 36
	v_lshlrev_b64 v[74:75], 12, v[74:75]
	v_readlane_b32 s3, v252, 37
	s_nop 1
	v_lshl_add_u64 v[74:75], s[2:3], 0, v[74:75]
	v_lshl_add_u64 v[78:79], v[2:3], 1, v[74:75]
	s_waitcnt vmcnt(15)
	v_lshlrev_b32_e32 v80, 16, v188
	v_and_b32_e32 v81, 0xffff0000, v188
	v_lshlrev_b32_e32 v74, 16, v189
	v_and_b32_e32 v75, 0xffff0000, v189
	v_lshlrev_b32_e32 v82, 16, v190
	v_and_b32_e32 v83, 0xffff0000, v190
	v_lshlrev_b32_e32 v76, 16, v191
	v_and_b32_e32 v77, 0xffff0000, v191
	v_pk_add_f32 v[74:75], v[70:71], v[74:75]
	v_pk_add_f32 v[80:81], v[68:69], v[80:81]
	v_pk_add_f32 v[76:77], v[66:67], v[76:77]
	v_pk_add_f32 v[82:83], v[64:65], v[82:83]
	v_cvt_pk_bf16_f32 v64, v80, v81
	v_cvt_pk_bf16_f32 v65, v74, v75
	s_waitcnt lgkmcnt(0)
	v_mul_f32_e32 v73, v81, v81
	v_cvt_pk_bf16_f32 v66, v82, v83
	v_cvt_pk_bf16_f32 v67, v76, v77
	v_mul_f32_e32 v75, v75, v75
	v_mul_f32_e32 v81, v83, v83
	v_fmac_f32_e32 v73, v80, v80
	v_fmac_f32_e32 v75, v74, v74
	v_mul_f32_e32 v77, v77, v77
	v_fmac_f32_e32 v81, v82, v82
	v_add_f32_e32 v73, v73, v75
	v_fmac_f32_e32 v77, v76, v76
	v_add_f32_e32 v73, v81, v73
	v_add_f32_e32 v73, v77, v73
	global_store_dwordx4 v[78:79], v[64:67], off nt
	s_waitcnt vmcnt(15)
	v_lshlrev_b32_e32 v74, 16, v192
	v_and_b32_e32 v75, 0xffff0000, v192
	v_lshlrev_b32_e32 v68, 16, v193
	v_and_b32_e32 v69, 0xffff0000, v193
	v_lshlrev_b32_e32 v76, 16, v194
	v_and_b32_e32 v77, 0xffff0000, v194
	v_lshlrev_b32_e32 v70, 16, v195
	v_and_b32_e32 v71, 0xffff0000, v195
	v_pk_add_f32 v[62:63], v[62:63], v[68:69]
	v_pk_add_f32 v[60:61], v[60:61], v[74:75]
	v_pk_add_f32 v[68:69], v[58:59], v[70:71]
	v_pk_add_f32 v[70:71], v[56:57], v[76:77]
	v_mul_f32_e32 v56, v61, v61
	v_mul_f32_e32 v57, v63, v63
	v_mul_f32_e32 v58, v71, v71
	v_fmac_f32_e32 v56, v60, v60
	v_fmac_f32_e32 v57, v62, v62
	v_mul_f32_e32 v59, v69, v69
	v_fmac_f32_e32 v58, v70, v70
	v_add_f32_e32 v56, v56, v57
	v_add_f32_e32 v56, v58, v56
	v_fmac_f32_e32 v59, v68, v68
	v_add_f32_e32 v56, v59, v56
	v_add_f32_e32 v56, v73, v56
	ds_bpermute_b32 v57, v128, v56
	v_cvt_pk_bf16_f32 v58, v60, v61
	v_cvt_pk_bf16_f32 v59, v62, v63
	v_cvt_pk_bf16_f32 v60, v70, v71
	v_cvt_pk_bf16_f32 v61, v68, v69
	s_waitcnt lgkmcnt(0)
	v_add_f32_e32 v56, v56, v57
	ds_bpermute_b32 v57, v120, v56
	global_store_dwordx4 v[78:79], v[58:61], off offset:256 nt
	s_and_saveexec_b64 s[2:3], vcc
	s_cbranch_execz .LBB0_217
	v_lshl_add_u32 v58, v72, 4, s5
	s_waitcnt lgkmcnt(0)
	v_add_f32_e32 v56, v56, v57
	ds_write_b32 v58, v56
; __device__ __forceinline__ unsigned cvt_pk_bf16(float lo, float hi) { unsigned r; asm volatile("v_cvt_pk_bf16_f32 %0, %1, %2" : "=v"(r) : "v"(lo), "v"(hi)); return r; }
;     __device__ __forceinline__ void fused(f32x4 (&acc)[2][2][4][2], const Unit& u, int wr, int wc, int fr, int fq, PG8_LAS unsigned char* lds, int wid, int lane) const {
;     ...
;         for (int ai = 0; ai < 2; ++ai)
; #pragma unroll
;             for (int m = 0; m < 4; ++m) { const int rl = ai * HALF + wr * 64 + m * 16 + fr; const size_t off = (size_t)(u.pm * BM + rl) * ldc + col0; float q = 0.f;
; #pragma unroll
;                 for (int bj = 0; bj < 2; ++bj) { const u32x4 hb = *(const u32x4*)(xb + off + bj * HALF);
;                     const f32x4 b0 = (f32x4){__uint_as_float(hb.x << 16), __uint_as_float(hb.x & 0xffff0000u), __uint_as_float(hb.y << 16), __uint_as_float(hb.y & 0xffff0000u)};
;                     const f32x4 b1 = (f32x4){__uint_as_float(hb.z << 16), __uint_as_float(hb.z & 0xffff0000u), __uint_as_float(hb.w << 16), __uint_as_float(hb.w & 0xffff0000u)};
;                     const f32x4 v0 = b0 + acc[ai][bj][m][0], v1 = b1 + acc[ai][bj][m][1];
;                     u32x4 w; w.x = cvt_pk_bf16(v0[0], v0[1]); w.y = cvt_pk_bf16(v0[2], v0[3]); w.z = cvt_pk_bf16(v1[0], v1[1]); w.w = cvt_pk_bf16(v1[2], v1[3]);
;                     *(u32x4*)(xb + off + bj * HALF) = w;
;                     q += (v0[0] * v0[0] + v0[1] * v0[1]) + (v0[2] * v0[2] + v0[3] * v0[3]) + (v1[0] * v1[0] + v1[1] * v1[1]) + (v1[2] * v1[2] + v1[3] * v1[3]); }
;                 q += __shfl_xor(q, 16); q += __shfl_xor(q, 32);
;                 if (fq == 0) P[rl * 4 + wc] = q; }
.LBB0_217:
	s_or_b64 exec, exec, s[2:3]
	v_add_u32_e32 v56, 0x90, v148
	v_add_u32_e32 v58, s4, v56
	v_ashrrev_i32_e32 v59, 31, v58
	v_readlane_b32 s2, v252, 36
	v_lshlrev_b64 v[58:59], 12, v[58:59]
	v_readlane_b32 s3, v252, 37
	s_nop 1
	v_lshl_add_u64 v[58:59], s[2:3], 0, v[58:59]
	v_lshl_add_u64 v[62:63], v[2:3], 1, v[58:59]
	s_waitcnt vmcnt(15)
	v_lshlrev_b32_e32 v64, 16, v196
	v_and_b32_e32 v65, 0xffff0000, v196
	v_lshlrev_b32_e32 v58, 16, v197
	v_and_b32_e32 v59, 0xffff0000, v197
	v_lshlrev_b32_e32 v66, 16, v198
	v_and_b32_e32 v67, 0xffff0000, v198
	v_lshlrev_b32_e32 v60, 16, v199
	v_and_b32_e32 v61, 0xffff0000, v199
	v_pk_add_f32 v[58:59], v[54:55], v[58:59]
	v_pk_add_f32 v[64:65], v[52:53], v[64:65]
	v_pk_add_f32 v[60:61], v[50:51], v[60:61]
	v_pk_add_f32 v[66:67], v[48:49], v[66:67]
	v_cvt_pk_bf16_f32 v48, v64, v65
	v_cvt_pk_bf16_f32 v49, v58, v59
	s_waitcnt lgkmcnt(0)
	v_mul_f32_e32 v57, v65, v65
	v_cvt_pk_bf16_f32 v50, v66, v67
	v_cvt_pk_bf16_f32 v51, v60, v61
	v_mul_f32_e32 v59, v59, v59
	v_mul_f32_e32 v65, v67, v67
	v_fmac_f32_e32 v57, v64, v64
	v_fmac_f32_e32 v59, v58, v58
	v_mul_f32_e32 v61, v61, v61
	v_fmac_f32_e32 v65, v66, v66
	v_add_f32_e32 v57, v57, v59
	v_fmac_f32_e32 v61, v60, v60
	v_add_f32_e32 v57, v65, v57
	v_add_f32_e32 v57, v61, v57
	global_store_dwordx4 v[62:63], v[48:51], off nt
	s_waitcnt vmcnt(15)
	v_lshlrev_b32_e32 v58, 16, v200
	v_and_b32_e32 v59, 0xffff0000, v200
	v_lshlrev_b32_e32 v52, 16, v201
	v_and_b32_e32 v53, 0xffff0000, v201
	v_lshlrev_b32_e32 v60, 16, v202
	v_and_b32_e32 v61, 0xffff0000, v202
	v_lshlrev_b32_e32 v54, 16, v203
	v_and_b32_e32 v55, 0xffff0000, v203
	v_pk_add_f32 v[46:47], v[46:47], v[52:53]
	v_pk_add_f32 v[44:45], v[44:45], v[58:59]
	v_pk_add_f32 v[52:53], v[42:43], v[54:55]
	v_pk_add_f32 v[54:55], v[40:41], v[60:61]
	v_mul_f32_e32 v40, v45, v45
	v_mul_f32_e32 v41, v47, v47
	v_mul_f32_e32 v42, v55, v55
	v_fmac_f32_e32 v40, v44, v44
	v_fmac_f32_e32 v41, v46, v46
	v_mul_f32_e32 v43, v53, v53
	v_fmac_f32_e32 v42, v54, v54
	v_add_f32_e32 v40, v40, v41
	v_add_f32_e32 v40, v42, v40
	v_fmac_f32_e32 v43, v52, v52
	v_add_f32_e32 v40, v43, v40
	v_add_f32_e32 v40, v57, v40
	ds_bpermute_b32 v41, v128, v40
	v_cvt_pk_bf16_f32 v42, v44, v45
	v_cvt_pk_bf16_f32 v43, v46, v47
	v_cvt_pk_bf16_f32 v44, v54, v55
	v_cvt_pk_bf16_f32 v45, v52, v53
	s_waitcnt lgkmcnt(0)
	v_add_f32_e32 v40, v40, v41
	ds_bpermute_b32 v41, v120, v40
	global_store_dwordx4 v[62:63], v[42:45], off offset:256 nt
	s_and_saveexec_b64 s[2:3], vcc
	s_cbranch_execz .LBB0_219
	v_lshl_add_u32 v42, v56, 4, s5
	s_waitcnt lgkmcnt(0)
	v_add_f32_e32 v40, v40, v41
	ds_write_b32 v42, v40
; __device__ __forceinline__ unsigned cvt_pk_bf16(float lo, float hi) { unsigned r; asm volatile("v_cvt_pk_bf16_f32 %0, %1, %2" : "=v"(r) : "v"(lo), "v"(hi)); return r; }
;     __device__ __forceinline__ void fused(f32x4 (&acc)[2][2][4][2], const Unit& u, int wr, int wc, int fr, int fq, PG8_LAS unsigned char* lds, int wid, int lane) const {
;     ...
;         for (int ai = 0; ai < 2; ++ai)
; #pragma unroll
;             for (int m = 0; m < 4; ++m) { const int rl = ai * HALF + wr * 64 + m * 16 + fr; const size_t off = (size_t)(u.pm * BM + rl) * ldc + col0; float q = 0.f;
; #pragma unroll
;                 for (int bj = 0; bj < 2; ++bj) { const u32x4 hb = *(const u32x4*)(xb + off + bj * HALF);
;                     const f32x4 b0 = (f32x4){__uint_as_float(hb.x << 16), __uint_as_float(hb.x & 0xffff0000u), __uint_as_float(hb.y << 16), __uint_as_float(hb.y & 0xffff0000u)};
;                     const f32x4 b1 = (f32x4){__uint_as_float(hb.z << 16), __uint_as_float(hb.z & 0xffff0000u), __uint_as_float(hb.w << 16), __uint_as_float(hb.w & 0xffff0000u)};
;                     const f32x4 v0 = b0 + acc[ai][bj][m][0], v1 = b1 + acc[ai][bj][m][1];
;                     u32x4 w; w.x = cvt_pk_bf16(v0[0], v0[1]); w.y = cvt_pk_bf16(v0[2], v0[3]); w.z = cvt_pk_bf16(v1[0], v1[1]); w.w = cvt_pk_bf16(v1[2], v1[3]);
;                     *(u32x4*)(xb + off + bj * HALF) = w;
;                     q += (v0[0] * v0[0] + v0[1] * v0[1]) + (v0[2] * v0[2] + v0[3] * v0[3]) + (v1[0] * v1[0] + v1[1] * v1[1]) + (v1[2] * v1[2] + v1[3] * v1[3]); }
;                 q += __shfl_xor(q, 16); q += __shfl_xor(q, 32);
;                 if (fq == 0) P[rl * 4 + wc] = q; }
.LBB0_219:
	s_or_b64 exec, exec, s[2:3]
	v_add_u32_e32 v40, 0xa0, v148
	v_add_u32_e32 v42, s4, v40
	v_ashrrev_i32_e32 v43, 31, v42
	v_readlane_b32 s2, v252, 36
	v_lshlrev_b64 v[42:43], 12, v[42:43]
	v_readlane_b32 s3, v252, 37
	s_nop 1
	v_lshl_add_u64 v[42:43], s[2:3], 0, v[42:43]
	v_lshl_add_u64 v[46:47], v[2:3], 1, v[42:43]
	s_waitcnt vmcnt(15)
	v_lshlrev_b32_e32 v48, 16, v204
	v_and_b32_e32 v49, 0xffff0000, v204
	v_lshlrev_b32_e32 v42, 16, v205
	v_and_b32_e32 v43, 0xffff0000, v205
	v_lshlrev_b32_e32 v50, 16, v206
	v_and_b32_e32 v51, 0xffff0000, v206
	v_lshlrev_b32_e32 v44, 16, v207
	v_and_b32_e32 v45, 0xffff0000, v207
	v_pk_add_f32 v[42:43], v[38:39], v[42:43]
	v_pk_add_f32 v[48:49], v[36:37], v[48:49]
	v_pk_add_f32 v[44:45], v[34:35], v[44:45]
	v_pk_add_f32 v[50:51], v[32:33], v[50:51]
	v_cvt_pk_bf16_f32 v32, v48, v49
	v_cvt_pk_bf16_f32 v33, v42, v43
	s_waitcnt lgkmcnt(0)
	v_mul_f32_e32 v41, v49, v49
	v_cvt_pk_bf16_f32 v34, v50, v51
	v_cvt_pk_bf16_f32 v35, v44, v45
	v_mul_f32_e32 v43, v43, v43
	v_mul_f32_e32 v49, v51, v51
	v_fmac_f32_e32 v41, v48, v48
	v_fmac_f32_e32 v43, v42, v42
	v_mul_f32_e32 v45, v45, v45
	v_fmac_f32_e32 v49, v50, v50
	v_add_f32_e32 v41, v41, v43
	v_fmac_f32_e32 v45, v44, v44
	v_add_f32_e32 v41, v49, v41
	v_add_f32_e32 v41, v45, v41
	global_store_dwordx4 v[46:47], v[32:35], off nt
	s_waitcnt vmcnt(15)
	v_lshlrev_b32_e32 v42, 16, v224
	v_and_b32_e32 v43, 0xffff0000, v224
	v_lshlrev_b32_e32 v36, 16, v225
	v_and_b32_e32 v37, 0xffff0000, v225
	v_lshlrev_b32_e32 v44, 16, v226
	v_and_b32_e32 v45, 0xffff0000, v226
	v_lshlrev_b32_e32 v38, 16, v227
	v_and_b32_e32 v39, 0xffff0000, v227
	v_pk_add_f32 v[30:31], v[30:31], v[36:37]
	v_pk_add_f32 v[28:29], v[28:29], v[42:43]
	v_pk_add_f32 v[36:37], v[26:27], v[38:39]
	v_pk_add_f32 v[38:39], v[24:25], v[44:45]
	v_mul_f32_e32 v24, v29, v29
	v_mul_f32_e32 v25, v31, v31
	v_mul_f32_e32 v26, v39, v39
	v_fmac_f32_e32 v24, v28, v28
	v_fmac_f32_e32 v25, v30, v30
	v_mul_f32_e32 v27, v37, v37
	v_fmac_f32_e32 v26, v38, v38
	v_add_f32_e32 v24, v24, v25
	v_add_f32_e32 v24, v26, v24
	v_fmac_f32_e32 v27, v36, v36
	v_add_f32_e32 v24, v27, v24
	v_add_f32_e32 v24, v41, v24
	ds_bpermute_b32 v25, v128, v24
	v_cvt_pk_bf16_f32 v26, v28, v29
	v_cvt_pk_bf16_f32 v27, v30, v31
	v_cvt_pk_bf16_f32 v28, v38, v39
	v_cvt_pk_bf16_f32 v29, v36, v37
	s_waitcnt lgkmcnt(0)
	v_add_f32_e32 v24, v24, v25
	ds_bpermute_b32 v25, v120, v24
	global_store_dwordx4 v[46:47], v[26:29], off offset:256 nt
	s_and_saveexec_b64 s[2:3], vcc
	s_cbranch_execz .LBB0_221
	v_lshl_add_u32 v26, v40, 4, s5
	s_waitcnt lgkmcnt(0)
	v_add_f32_e32 v24, v24, v25
	ds_write_b32 v26, v24
.LBB0_221:
	s_or_b64 exec, exec, s[2:3]
	v_add_u32_e32 v24, 0xb0, v148
	v_add_u32_e32 v26, s4, v24
	v_ashrrev_i32_e32 v27, 31, v26
	v_readlane_b32 s2, v252, 36
	v_lshlrev_b64 v[26:27], 12, v[26:27]
	v_readlane_b32 s3, v252, 37
	s_nop 1
	v_lshl_add_u64 v[26:27], s[2:3], 0, v[26:27]
	v_lshl_add_u64 v[30:31], v[2:3], 1, v[26:27]
	s_waitcnt vmcnt(15)
	v_lshlrev_b32_e32 v2, 16, v228
	v_and_b32_e32 v3, 0xffff0000, v228
	v_lshlrev_b32_e32 v26, 16, v229
	v_and_b32_e32 v27, 0xffff0000, v229
	v_lshlrev_b32_e32 v32, 16, v230
	v_and_b32_e32 v33, 0xffff0000, v230
	v_lshlrev_b32_e32 v28, 16, v231
	v_and_b32_e32 v29, 0xffff0000, v231
	v_pk_add_f32 v[26:27], v[22:23], v[26:27]
	v_pk_add_f32 v[2:3], v[20:21], v[2:3]
	v_pk_add_f32 v[28:29], v[18:19], v[28:29]
	v_pk_add_f32 v[32:33], v[16:17], v[32:33]
	v_cvt_pk_bf16_f32 v16, v2, v3
	v_cvt_pk_bf16_f32 v17, v26, v27
	v_mul_f32_e32 v3, v3, v3
	v_cvt_pk_bf16_f32 v18, v32, v33
	v_cvt_pk_bf16_f32 v19, v28, v29
	s_waitcnt lgkmcnt(0)
	v_mul_f32_e32 v25, v27, v27
	v_mul_f32_e32 v27, v33, v33
	v_fmac_f32_e32 v3, v2, v2
	v_fmac_f32_e32 v25, v26, v26
	v_mul_f32_e32 v29, v29, v29
	v_fmac_f32_e32 v27, v32, v32
	v_add_f32_e32 v2, v3, v25
	v_fmac_f32_e32 v29, v28, v28
	v_add_f32_e32 v2, v27, v2
	v_add_f32_e32 v25, v29, v2
	global_store_dwordx4 v[30:31], v[16:19], off nt
	s_waitcnt vmcnt(15)
	v_lshlrev_b32_e32 v2, 16, v232
	v_and_b32_e32 v3, 0xffff0000, v232
	v_lshlrev_b32_e32 v20, 16, v233
	v_and_b32_e32 v21, 0xffff0000, v233
	v_lshlrev_b32_e32 v26, 16, v234
	v_and_b32_e32 v27, 0xffff0000, v234
	v_lshlrev_b32_e32 v22, 16, v235
	v_and_b32_e32 v23, 0xffff0000, v235
	v_pk_add_f32 v[14:15], v[14:15], v[20:21]
	v_pk_add_f32 v[2:3], v[12:13], v[2:3]
	v_pk_add_f32 v[12:13], v[10:11], v[22:23]
	v_pk_add_f32 v[10:11], v[8:9], v[26:27]
	v_mul_f32_e32 v8, v3, v3
	v_mul_f32_e32 v9, v15, v15
	v_mul_f32_e32 v20, v11, v11
	v_fmac_f32_e32 v8, v2, v2
	v_fmac_f32_e32 v9, v14, v14
	v_mul_f32_e32 v21, v13, v13
	v_fmac_f32_e32 v20, v10, v10
	v_add_f32_e32 v8, v8, v9
	v_add_f32_e32 v8, v20, v8
	v_fmac_f32_e32 v21, v12, v12
	v_add_f32_e32 v8, v21, v8
	v_add_f32_e32 v9, v25, v8
	ds_bpermute_b32 v20, v128, v9
	v_cvt_pk_bf16_f32 v8, v2, v3
	s_waitcnt lgkmcnt(0)
	v_add_f32_e32 v2, v9, v20
	ds_bpermute_b32 v3, v120, v2
	v_cvt_pk_bf16_f32 v9, v14, v15
	v_cvt_pk_bf16_f32 v10, v10, v11
	v_cvt_pk_bf16_f32 v11, v12, v13
	global_store_dwordx4 v[30:31], v[8:11], off offset:256 nt
	s_and_saveexec_b64 s[2:3], vcc
	s_cbranch_execz .LBB0_223
	v_lshl_add_u32 v8, v24, 4, s5
	s_waitcnt lgkmcnt(0)
	v_add_f32_e32 v2, v2, v3
	ds_write_b32 v8, v2

; #define PG8_LAS __attribute__((address_space(3)))
; __device__ __forceinline__ unsigned cvt_pk_bf16(float lo, float hi) { unsigned r; asm volatile("v_cvt_pk_bf16_f32 %0, %1, %2" : "=v"(r) : "v"(lo), "v"(hi)); return r; }
; #define PG8_WAIT_V(n) asm volatile("s_waitcnt vmcnt(" #n ")" ::: "memory")
; #define PG8_BAR __builtin_amdgcn_s_barrier()
;     __device__ __forceinline__ void fused(f32x4 (&acc)[2][2][4][2], const Unit& u, int wr, int wc, int fr, int fq, PG8_LAS unsigned char* lds, int wid, int lane) const {
;         khook(acc, 0, wr, fr, lds);
;         PG8_LAS float* P = (PG8_LAS float*)lds;
;         const int col0 = u.pn * BM + wc * 32 + 8 * fq;
; #pragma unroll
;         for (int ai = 0; ai < 2; ++ai)
; #pragma unroll
;             for (int m = 0; m < 4; ++m) { const int rl = ai * HALF + wr * 64 + m * 16 + fr; const size_t off = (size_t)(u.pm * BM + rl) * ldc + col0; float q = 0.f;
; #pragma unroll
;                 for (int bj = 0; bj < 2; ++bj) { const u32x4 hb = *(const u32x4*)(xb + off + bj * HALF);
;                     const f32x4 b0 = (f32x4){__uint_as_float(hb.x << 16), __uint_as_float(hb.x & 0xffff0000u), __uint_as_float(hb.y << 16), __uint_as_float(hb.y & 0xffff0000u)};
;                     const f32x4 b1 = (f32x4){__uint_as_float(hb.z << 16), __uint_as_float(hb.z & 0xffff0000u), __uint_as_float(hb.w << 16), __uint_as_float(hb.w & 0xffff0000u)};
;                     const f32x4 v0 = b0 + acc[ai][bj][m][0], v1 = b1 + acc[ai][bj][m][1];
;                     u32x4 w; w.x = cvt_pk_bf16(v0[0], v0[1]); w.y = cvt_pk_bf16(v0[2], v0[3]); w.z = cvt_pk_bf16(v1[0], v1[1]); w.w = cvt_pk_bf16(v1[2], v1[3]);
;                     *(u32x4*)(xb + off + bj * HALF) = w;
;                     q += (v0[0] * v0[0] + v0[1] * v0[1]) + (v0[2] * v0[2] + v0[3] * v0[3]) + (v1[0] * v1[0] + v1[1] * v1[1]) + (v1[2] * v1[2] + v1[3] * v1[3]); }
;                 q += __shfl_xor(q, 16); q += __shfl_xor(q, 32);
;                 if (fq == 0) P[rl * 4 + wc] = q; }
; template <class Epi, class Sched, bool ALIGN_EPI = false, bool SP2 = false>
; __device__ __forceinline__ void gemm_phase(PG8_LAS unsigned char* lds, const Gemm g, const Sched& S, const Epi& E) {
;     ...
;     PG8_WAIT_V(0);
;     if constexpr (!ALIGN_EPI) { if (wr == 0) PG8_BAR; }
;     PG8_BAR;
;     if constexpr (Epi::AFTER_DRAIN) { E.fused(acc, cur, wr, wc, fr, fq, lds, wid, lane); S.done(cur); }
.LBB0_254:
	s_lshl_b32 s2, s45, 5
	s_lshl_b32 s3, s0, 8
	s_or_b32 s2, s3, s2
	s_lshl_b32 s3, s44, 8
	v_lshrrev_b32_e32 v208, 1, v145
	v_and_or_b32 v208, v208, 24, s2
	v_add_u32_e32 v209, s3, v144
	v_lshlrev_b32_e32 v209, 12, v209
	v_lshl_add_u32 v209, v208, 1, v209
	v_readlane_b32 s2, v252, 36
	v_readlane_b32 s3, v252, 37
	s_nop 4
	global_load_dwordx4 v[158:161], v209, s[2:3] nt
	global_load_dwordx4 v[162:165], v209, s[2:3] offset:256 nt
	v_add_u32_e32 v209, 0x10000, v209
	global_load_dwordx4 v[166:169], v209, s[2:3] nt
	global_load_dwordx4 v[170:173], v209, s[2:3] offset:256 nt
	v_add_u32_e32 v209, 0x10000, v209
	global_load_dwordx4 v[174:177], v209, s[2:3] nt
	global_load_dwordx4 v[178:181], v209, s[2:3] offset:256 nt
	v_add_u32_e32 v209, 0x10000, v209
	global_load_dwordx4 v[184:187], v209, s[2:3] nt
	global_load_dwordx4 v[188:191], v209, s[2:3] offset:256 nt
	v_add_u32_e32 v209, 0x50000, v209
	global_load_dwordx4 v[192:195], v209, s[2:3] nt
	global_load_dwordx4 v[196:199], v209, s[2:3] offset:256 nt
	v_add_u32_e32 v209, 0x10000, v209
	global_load_dwordx4 v[200:203], v209, s[2:3] nt
	global_load_dwordx4 v[204:207], v209, s[2:3] offset:256 nt
	v_add_u32_e32 v209, 0x10000, v209
	global_load_dwordx4 v[224:227], v209, s[2:3] nt
	global_load_dwordx4 v[228:231], v209, s[2:3] offset:256 nt
	v_add_u32_e32 v209, 0x10000, v209
	global_load_dwordx4 v[232:235], v209, s[2:3] nt
	global_load_dwordx4 v[236:239], v209, s[2:3] offset:256 nt
	s_waitcnt vmcnt(16)
	s_cmpk_gt_u32 s1, 0xff
	s_cbranch_scc1 .LBB0_256
	s_barrier
.LBB0_256:
	s_lshl_b32 s2, s45, 5
	s_lshl_b32 s3, s0, 8
	s_lshl_b32 s4, s44, 8
	v_lshrrev_b32_e32 v0, 1, v145
	s_or_b32 s2, s3, s2
	v_add_u32_e32 v136, s4, v144
	v_and_or_b32 v2, v0, 24, s2
	v_ashrrev_i32_e32 v137, 31, v136
	v_readlane_b32 s2, v252, 36
	v_lshlrev_b64 v[136:137], 12, v[136:137]
	v_readlane_b32 s3, v252, 37
	v_ashrrev_i32_e32 v3, 31, v2
	s_barrier
	v_lshl_add_u64 v[136:137], s[2:3], 0, v[136:137]
	v_lshl_add_u64 v[152:153], v[2:3], 1, v[136:137]
	v_lshl_add_u32 v0, v146, 2, s73
	v_add_u32_e32 v0, 0x22c00, v0
	ds_read2_b32 v[142:143], v0 offset1:16
	ds_read2_b32 v[140:141], v0 offset0:32 offset1:48
	ds_read2_b32 v[138:139], v0 offset0:128 offset1:144
	ds_read2_b32 v[136:137], v0 offset0:160 offset1:176
	v_and_b32_e32 v0, 63, v145
	v_cmp_lt_i32_e32 vcc, v219, v214
	s_lshl_b32 s2, s45, 2
	s_add_i32 s5, s2, 0
	s_waitcnt vmcnt(15)
	v_lshlrev_b32_e32 v146, 16, v158
	v_and_b32_e32 v147, 0xffff0000, v158
	v_lshlrev_b32_e32 v148, 16, v159
	v_and_b32_e32 v149, 0xffff0000, v159
	v_lshlrev_b32_e32 v154, 16, v160
	v_and_b32_e32 v155, 0xffff0000, v160
	v_lshlrev_b32_e32 v150, 16, v161
	v_and_b32_e32 v151, 0xffff0000, v161
	s_waitcnt lgkmcnt(0)
	v_pk_fma_f32 v[134:135], v[134:135], v[142:143], v[148:149] op_sel_hi:[1,0,1]
	v_pk_fma_f32 v[156:157], v[132:133], v[142:143], v[146:147] op_sel_hi:[1,0,1]
	v_pk_fma_f32 v[150:151], v[130:131], v[142:143], v[150:151] op_sel_hi:[1,0,1]
	v_pk_fma_f32 v[154:155], v[128:129], v[142:143], v[154:155] op_sel_hi:[1,0,1]
	v_cvt_pk_bf16_f32 v130, v156, v157
	v_cvt_pk_bf16_f32 v131, v134, v135
	v_mul_f32_e32 v145, v157, v157
	v_cvt_pk_bf16_f32 v132, v154, v155
	v_cvt_pk_bf16_f32 v133, v150, v151
	v_mul_f32_e32 v135, v135, v135
	v_mul_f32_e32 v155, v155, v155
	v_fmac_f32_e32 v145, v156, v156
	v_fmac_f32_e32 v135, v134, v134
	v_mul_f32_e32 v151, v151, v151
	v_fmac_f32_e32 v155, v154, v154
	v_add_f32_e32 v134, v145, v135
	v_fmac_f32_e32 v151, v150, v150
	v_add_f32_e32 v134, v155, v134
	v_add_f32_e32 v145, v151, v134
	v_cndmask_b32_e32 v128, v213, v219, vcc
	v_lshlrev_b32_e32 v128, 2, v128
	v_cmp_lt_i32_e32 vcc, v220, v214
	global_store_dwordx4 v[152:153], v[130:133], off nt
	s_waitcnt vmcnt(15)
	v_lshlrev_b32_e32 v134, 16, v162
	v_and_b32_e32 v135, 0xffff0000, v162
	v_lshlrev_b32_e32 v146, 16, v163
	v_and_b32_e32 v147, 0xffff0000, v163
	v_lshlrev_b32_e32 v150, 16, v164
	v_and_b32_e32 v151, 0xffff0000, v164
	v_pk_fma_f32 v[126:127], v[126:127], v[142:143], v[146:147] op_sel_hi:[1,0,1]
	v_pk_fma_f32 v[124:125], v[124:125], v[142:143], v[134:135] op_sel_hi:[1,0,1]
	v_lshlrev_b32_e32 v148, 16, v165
	v_and_b32_e32 v149, 0xffff0000, v165
	v_pk_fma_f32 v[146:147], v[120:121], v[142:143], v[150:151] op_sel_hi:[1,0,1]
	v_mul_f32_e32 v120, v125, v125
	v_mul_f32_e32 v121, v127, v127
	v_pk_fma_f32 v[134:135], v[122:123], v[142:143], v[148:149] op_sel_hi:[1,0,1]
	v_mul_f32_e32 v122, v147, v147
	v_fmac_f32_e32 v120, v124, v124
	v_fmac_f32_e32 v121, v126, v126
	v_mul_f32_e32 v123, v135, v135
	v_fmac_f32_e32 v122, v146, v146
	v_add_f32_e32 v120, v120, v121
	v_fmac_f32_e32 v123, v134, v134
	v_add_f32_e32 v120, v122, v120
	v_add_f32_e32 v120, v123, v120
	v_add_f32_e32 v120, v145, v120
	ds_bpermute_b32 v121, v128, v120
	v_cndmask_b32_e32 v129, v213, v220, vcc
	v_cmp_gt_u32_e32 vcc, 16, v0
	v_cvt_pk_bf16_f32 v124, v124, v125
	v_cvt_pk_bf16_f32 v125, v126, v127
	s_waitcnt lgkmcnt(0)
	v_add_f32_e32 v121, v120, v121
	v_lshlrev_b32_e32 v120, 2, v129
	ds_bpermute_b32 v122, v120, v121
	v_cvt_pk_bf16_f32 v126, v146, v147
	v_cvt_pk_bf16_f32 v127, v134, v135
	global_store_dwordx4 v[152:153], v[124:127], off offset:256 nt
	s_and_saveexec_b64 s[2:3], vcc
	s_cbranch_execz .LBB0_258
	v_lshl_add_u32 v123, v144, 4, s5
	s_waitcnt lgkmcnt(0)
	v_add_f32_e32 v121, v121, v122
	ds_write_b32 v123, v121
; #define PG8_LAS __attribute__((address_space(3)))
; __device__ __forceinline__ unsigned cvt_pk_bf16(float lo, float hi) { unsigned r; asm volatile("v_cvt_pk_bf16_f32 %0, %1, %2" : "=v"(r) : "v"(lo), "v"(hi)); return r; }
;     __device__ __forceinline__ void khook(f32x4 (&acc)[2][2][4][2], int hb, int wr, int fr, PG8_LAS unsigned char* lds) const {
;     ...
;             for (int m = 0; m < 4; ++m) { const float r = RT[ai * HALF + m * 16];
; #pragma unroll
;                 for (int bj = 0; bj < 2; ++bj)
; #pragma unroll
;                     for (int n = 0; n < 2; ++n) acc[ai][bj][m][n] = acc[ai][bj][m][n] * r; } }
;     __device__ __forceinline__ void fused(f32x4 (&acc)[2][2][4][2], const Unit& u, int wr, int wc, int fr, int fq, PG8_LAS unsigned char* lds, int wid, int lane) const {
;         khook(acc, 0, wr, fr, lds);
;         PG8_LAS float* P = (PG8_LAS float*)lds;
;         const int col0 = u.pn * BM + wc * 32 + 8 * fq;
; #pragma unroll
;         for (int ai = 0; ai < 2; ++ai)
; #pragma unroll
;             for (int m = 0; m < 4; ++m) { const int rl = ai * HALF + wr * 64 + m * 16 + fr; const size_t off = (size_t)(u.pm * BM + rl) * ldc + col0; float q = 0.f;
; #pragma unroll
;                 for (int bj = 0; bj < 2; ++bj) { const u32x4 hb = *(const u32x4*)(xb + off + bj * HALF);
;                     const f32x4 b0 = (f32x4){__uint_as_float(hb.x << 16), __uint_as_float(hb.x & 0xffff0000u), __uint_as_float(hb.y << 16), __uint_as_float(hb.y & 0xffff0000u)};
;                     const f32x4 b1 = (f32x4){__uint_as_float(hb.z << 16), __uint_as_float(hb.z & 0xffff0000u), __uint_as_float(hb.w << 16), __uint_as_float(hb.w & 0xffff0000u)};
;                     const f32x4 v0 = b0 + acc[ai][bj][m][0], v1 = b1 + acc[ai][bj][m][1];
;                     u32x4 w; w.x = cvt_pk_bf16(v0[0], v0[1]); w.y = cvt_pk_bf16(v0[2], v0[3]); w.z = cvt_pk_bf16(v1[0], v1[1]); w.w = cvt_pk_bf16(v1[2], v1[3]);
;                     *(u32x4*)(xb + off + bj * HALF) = w;
;                     q += (v0[0] * v0[0] + v0[1] * v0[1]) + (v0[2] * v0[2] + v0[3] * v0[3]) + (v1[0] * v1[0] + v1[1] * v1[1]) + (v1[2] * v1[2] + v1[3] * v1[3]); }
;                 q += __shfl_xor(q, 16); q += __shfl_xor(q, 32);
;                 if (fq == 0) P[rl * 4 + wc] = q; }
.LBB0_258:
	s_or_b64 exec, exec, s[2:3]
	v_or_b32_e32 v121, 16, v144
	s_waitcnt lgkmcnt(0)
	v_add_u32_e32 v122, s4, v121
	v_ashrrev_i32_e32 v123, 31, v122
	v_readlane_b32 s2, v252, 36
	v_lshlrev_b64 v[122:123], 12, v[122:123]
	v_readlane_b32 s3, v252, 37
	v_mov_b32_e32 v130, v143
	s_nop 0
	v_lshl_add_u64 v[122:123], s[2:3], 0, v[122:123]
	v_lshl_add_u64 v[126:127], v[2:3], 1, v[122:123]
	s_waitcnt vmcnt(15)
	v_lshlrev_b32_e32 v132, 16, v166
	v_and_b32_e32 v133, 0xffff0000, v166
	v_lshlrev_b32_e32 v122, 16, v167
	v_and_b32_e32 v123, 0xffff0000, v167
	v_lshlrev_b32_e32 v134, 16, v168
	v_and_b32_e32 v135, 0xffff0000, v168
	v_lshlrev_b32_e32 v124, 16, v169
	v_and_b32_e32 v125, 0xffff0000, v169
	v_pk_fma_f32 v[122:123], v[118:119], v[130:131], v[122:123] op_sel_hi:[1,0,1]
	v_pk_fma_f32 v[132:133], v[116:117], v[130:131], v[132:133] op_sel_hi:[1,0,1]
	v_pk_fma_f32 v[124:125], v[114:115], v[130:131], v[124:125] op_sel_hi:[1,0,1]
	v_pk_fma_f32 v[134:135], v[112:113], v[130:131], v[134:135] op_sel_hi:[1,0,1]
	v_cvt_pk_bf16_f32 v112, v132, v133
	v_cvt_pk_bf16_f32 v113, v122, v123
	v_mul_f32_e32 v129, v133, v133
	v_cvt_pk_bf16_f32 v114, v134, v135
	v_cvt_pk_bf16_f32 v115, v124, v125
	v_mul_f32_e32 v123, v123, v123
	v_mul_f32_e32 v131, v135, v135
	v_fmac_f32_e32 v129, v132, v132
	v_fmac_f32_e32 v123, v122, v122
	v_mul_f32_e32 v125, v125, v125
	v_fmac_f32_e32 v131, v134, v134
	v_add_f32_e32 v122, v129, v123
	v_fmac_f32_e32 v125, v124, v124
	v_add_f32_e32 v122, v131, v122
	v_add_f32_e32 v129, v125, v122
	global_store_dwordx4 v[126:127], v[112:115], off nt
	s_waitcnt vmcnt(15)
	v_lshlrev_b32_e32 v122, 16, v170
	v_and_b32_e32 v123, 0xffff0000, v170
	v_lshlrev_b32_e32 v116, 16, v171
	v_and_b32_e32 v117, 0xffff0000, v171
	v_lshlrev_b32_e32 v124, 16, v172
	v_and_b32_e32 v125, 0xffff0000, v172
	v_lshlrev_b32_e32 v118, 16, v173
	v_and_b32_e32 v119, 0xffff0000, v173
	v_pk_fma_f32 v[110:111], v[110:111], v[130:131], v[116:117] op_sel_hi:[1,0,1]
	v_pk_fma_f32 v[108:109], v[108:109], v[130:131], v[122:123] op_sel_hi:[1,0,1]
	v_pk_fma_f32 v[116:117], v[106:107], v[130:131], v[118:119] op_sel_hi:[1,0,1]
	v_pk_fma_f32 v[118:119], v[104:105], v[130:131], v[124:125] op_sel_hi:[1,0,1]
	v_mul_f32_e32 v104, v109, v109
	v_mul_f32_e32 v105, v111, v111
	v_mul_f32_e32 v106, v119, v119
	v_fmac_f32_e32 v104, v108, v108
	v_fmac_f32_e32 v105, v110, v110
	v_mul_f32_e32 v107, v117, v117
	v_fmac_f32_e32 v106, v118, v118
	v_add_f32_e32 v104, v104, v105
	v_add_f32_e32 v104, v106, v104
	v_fmac_f32_e32 v107, v116, v116
	v_add_f32_e32 v104, v107, v104
	v_add_f32_e32 v104, v129, v104
	ds_bpermute_b32 v105, v128, v104
	v_cvt_pk_bf16_f32 v106, v108, v109
	v_cvt_pk_bf16_f32 v107, v110, v111
	v_cvt_pk_bf16_f32 v108, v118, v119
	v_cvt_pk_bf16_f32 v109, v116, v117
	s_waitcnt lgkmcnt(0)
	v_add_f32_e32 v104, v104, v105
	ds_bpermute_b32 v105, v120, v104
	global_store_dwordx4 v[126:127], v[106:109], off offset:256 nt
	s_and_saveexec_b64 s[2:3], vcc
	s_cbranch_execz .LBB0_260
	v_lshl_add_u32 v106, v121, 4, s5
	s_waitcnt lgkmcnt(0)
	v_add_f32_e32 v104, v104, v105
	ds_write_b32 v106, v104
.LBB0_260:
	s_or_b64 exec, exec, s[2:3]
	v_or_b32_e32 v104, 32, v144
	v_add_u32_e32 v106, s4, v104
	v_ashrrev_i32_e32 v107, 31, v106
	v_readlane_b32 s2, v252, 36
	v_lshlrev_b64 v[106:107], 12, v[106:107]
	v_readlane_b32 s3, v252, 37
	s_nop 1
	v_lshl_add_u64 v[106:107], s[2:3], 0, v[106:107]
	v_lshl_add_u64 v[110:111], v[2:3], 1, v[106:107]
	s_waitcnt vmcnt(15)
	v_lshlrev_b32_e32 v112, 16, v174
	v_and_b32_e32 v113, 0xffff0000, v174
	v_lshlrev_b32_e32 v106, 16, v175
	v_and_b32_e32 v107, 0xffff0000, v175
	v_lshlrev_b32_e32 v114, 16, v176
	v_and_b32_e32 v115, 0xffff0000, v176
	v_lshlrev_b32_e32 v108, 16, v177
	v_and_b32_e32 v109, 0xffff0000, v177
	v_pk_fma_f32 v[106:107], v[102:103], v[140:141], v[106:107] op_sel_hi:[1,0,1]
	v_pk_fma_f32 v[112:113], v[100:101], v[140:141], v[112:113] op_sel_hi:[1,0,1]
	v_pk_fma_f32 v[108:109], v[98:99], v[140:141], v[108:109] op_sel_hi:[1,0,1]
	v_pk_fma_f32 v[114:115], v[96:97], v[140:141], v[114:115] op_sel_hi:[1,0,1]
	v_cvt_pk_bf16_f32 v96, v112, v113
	v_cvt_pk_bf16_f32 v97, v106, v107
	s_waitcnt lgkmcnt(0)
	v_mul_f32_e32 v105, v113, v113
	v_cvt_pk_bf16_f32 v98, v114, v115
	v_cvt_pk_bf16_f32 v99, v108, v109
	v_mul_f32_e32 v107, v107, v107
	v_mul_f32_e32 v113, v115, v115
	v_fmac_f32_e32 v105, v112, v112
	v_fmac_f32_e32 v107, v106, v106
	v_mul_f32_e32 v109, v109, v109
	v_fmac_f32_e32 v113, v114, v114
	v_add_f32_e32 v105, v105, v107
	v_fmac_f32_e32 v109, v108, v108
	v_add_f32_e32 v105, v113, v105
	v_add_f32_e32 v105, v109, v105
	global_store_dwordx4 v[110:111], v[96:99], off nt
	s_waitcnt vmcnt(15)
	v_lshlrev_b32_e32 v106, 16, v178
	v_and_b32_e32 v107, 0xffff0000, v178
	v_lshlrev_b32_e32 v100, 16, v179
	v_and_b32_e32 v101, 0xffff0000, v179
	v_lshlrev_b32_e32 v108, 16, v180
	v_and_b32_e32 v109, 0xffff0000, v180
	v_lshlrev_b32_e32 v102, 16, v181
	v_and_b32_e32 v103, 0xffff0000, v181
	v_pk_fma_f32 v[94:95], v[94:95], v[140:141], v[100:101] op_sel_hi:[1,0,1]
	v_pk_fma_f32 v[92:93], v[92:93], v[140:141], v[106:107] op_sel_hi:[1,0,1]
	v_pk_fma_f32 v[100:101], v[90:91], v[140:141], v[102:103] op_sel_hi:[1,0,1]
	v_pk_fma_f32 v[102:103], v[88:89], v[140:141], v[108:109] op_sel_hi:[1,0,1]
	v_mul_f32_e32 v88, v93, v93
	v_mul_f32_e32 v89, v95, v95
	v_mul_f32_e32 v90, v103, v103
	v_fmac_f32_e32 v88, v92, v92
	v_fmac_f32_e32 v89, v94, v94
	v_mul_f32_e32 v91, v101, v101
	v_fmac_f32_e32 v90, v102, v102
	v_add_f32_e32 v88, v88, v89
	v_add_f32_e32 v88, v90, v88
	v_fmac_f32_e32 v91, v100, v100
	v_add_f32_e32 v88, v91, v88
	v_add_f32_e32 v88, v105, v88
	ds_bpermute_b32 v89, v128, v88
	v_cvt_pk_bf16_f32 v90, v92, v93
	v_cvt_pk_bf16_f32 v91, v94, v95
	v_cvt_pk_bf16_f32 v92, v102, v103
	v_cvt_pk_bf16_f32 v93, v100, v101
	s_waitcnt lgkmcnt(0)
	v_add_f32_e32 v88, v88, v89
	ds_bpermute_b32 v89, v120, v88
	global_store_dwordx4 v[110:111], v[90:93], off offset:256 nt
	s_and_saveexec_b64 s[2:3], vcc
	s_cbranch_execz .LBB0_262
	v_lshl_add_u32 v90, v104, 4, s5
	s_waitcnt lgkmcnt(0)
	v_add_f32_e32 v88, v88, v89
	ds_write_b32 v90, v88
; #define PG8_LAS __attribute__((address_space(3)))
; __device__ __forceinline__ unsigned cvt_pk_bf16(float lo, float hi) { unsigned r; asm volatile("v_cvt_pk_bf16_f32 %0, %1, %2" : "=v"(r) : "v"(lo), "v"(hi)); return r; }
;     __device__ __forceinline__ void khook(f32x4 (&acc)[2][2][4][2], int hb, int wr, int fr, PG8_LAS unsigned char* lds) const {
;     ...
;             for (int m = 0; m < 4; ++m) { const float r = RT[ai * HALF + m * 16];
; #pragma unroll
;                 for (int bj = 0; bj < 2; ++bj)
; #pragma unroll
;                     for (int n = 0; n < 2; ++n) acc[ai][bj][m][n] = acc[ai][bj][m][n] * r; } }
;     __device__ __forceinline__ void fused(f32x4 (&acc)[2][2][4][2], const Unit& u, int wr, int wc, int fr, int fq, PG8_LAS unsigned char* lds, int wid, int lane) const {
;         khook(acc, 0, wr, fr, lds);
;         PG8_LAS float* P = (PG8_LAS float*)lds;
;         const int col0 = u.pn * BM + wc * 32 + 8 * fq;
; #pragma unroll
;         for (int ai = 0; ai < 2; ++ai)
; #pragma unroll
;             for (int m = 0; m < 4; ++m) { const int rl = ai * HALF + wr * 64 + m * 16 + fr; const size_t off = (size_t)(u.pm * BM + rl) * ldc + col0; float q = 0.f;
; #pragma unroll
;                 for (int bj = 0; bj < 2; ++bj) { const u32x4 hb = *(const u32x4*)(xb + off + bj * HALF);
;                     const f32x4 b0 = (f32x4){__uint_as_float(hb.x << 16), __uint_as_float(hb.x & 0xffff0000u), __uint_as_float(hb.y << 16), __uint_as_float(hb.y & 0xffff0000u)};
;                     const f32x4 b1 = (f32x4){__uint_as_float(hb.z << 16), __uint_as_float(hb.z & 0xffff0000u), __uint_as_float(hb.w << 16), __uint_as_float(hb.w & 0xffff0000u)};
;                     const f32x4 v0 = b0 + acc[ai][bj][m][0], v1 = b1 + acc[ai][bj][m][1];
;                     u32x4 w; w.x = cvt_pk_bf16(v0[0], v0[1]); w.y = cvt_pk_bf16(v0[2], v0[3]); w.z = cvt_pk_bf16(v1[0], v1[1]); w.w = cvt_pk_bf16(v1[2], v1[3]);
;                     *(u32x4*)(xb + off + bj * HALF) = w;
;                     q += (v0[0] * v0[0] + v0[1] * v0[1]) + (v0[2] * v0[2] + v0[3] * v0[3]) + (v1[0] * v1[0] + v1[1] * v1[1]) + (v1[2] * v1[2] + v1[3] * v1[3]); }
;                 q += __shfl_xor(q, 16); q += __shfl_xor(q, 32);
;                 if (fq == 0) P[rl * 4 + wc] = q; }
.LBB0_262:
	s_or_b64 exec, exec, s[2:3]
	v_or_b32_e32 v88, 48, v144
	v_add_u32_e32 v90, s4, v88
	v_ashrrev_i32_e32 v91, 31, v90
	v_readlane_b32 s2, v252, 36
	v_lshlrev_b64 v[90:91], 12, v[90:91]
	v_readlane_b32 s3, v252, 37
	v_mov_b32_e32 v96, v141
	s_nop 0
	v_lshl_add_u64 v[90:91], s[2:3], 0, v[90:91]
	v_lshl_add_u64 v[94:95], v[2:3], 1, v[90:91]
	s_waitcnt vmcnt(15)
	v_lshlrev_b32_e32 v98, 16, v184
	v_and_b32_e32 v99, 0xffff0000, v184
	v_lshlrev_b32_e32 v90, 16, v185
	v_and_b32_e32 v91, 0xffff0000, v185
	v_lshlrev_b32_e32 v100, 16, v186
	v_and_b32_e32 v101, 0xffff0000, v186
	v_lshlrev_b32_e32 v92, 16, v187
	v_and_b32_e32 v93, 0xffff0000, v187
	v_pk_fma_f32 v[90:91], v[86:87], v[96:97], v[90:91] op_sel_hi:[1,0,1]
	v_pk_fma_f32 v[98:99], v[84:85], v[96:97], v[98:99] op_sel_hi:[1,0,1]
	v_pk_fma_f32 v[92:93], v[82:83], v[96:97], v[92:93] op_sel_hi:[1,0,1]
	v_pk_fma_f32 v[100:101], v[80:81], v[96:97], v[100:101] op_sel_hi:[1,0,1]
	v_cvt_pk_bf16_f32 v80, v98, v99
	v_cvt_pk_bf16_f32 v81, v90, v91
	s_waitcnt lgkmcnt(0)
	v_mul_f32_e32 v89, v99, v99
	v_cvt_pk_bf16_f32 v82, v100, v101
	v_cvt_pk_bf16_f32 v83, v92, v93
	v_mul_f32_e32 v91, v91, v91
	v_mul_f32_e32 v97, v101, v101
	v_fmac_f32_e32 v89, v98, v98
	v_fmac_f32_e32 v91, v90, v90
	v_mul_f32_e32 v93, v93, v93
	v_fmac_f32_e32 v97, v100, v100
	v_add_f32_e32 v89, v89, v91
	v_fmac_f32_e32 v93, v92, v92
	v_add_f32_e32 v89, v97, v89
	v_add_f32_e32 v89, v93, v89
	global_store_dwordx4 v[94:95], v[80:83], off nt
	s_waitcnt vmcnt(15)
	v_lshlrev_b32_e32 v90, 16, v188
	v_and_b32_e32 v91, 0xffff0000, v188
	v_lshlrev_b32_e32 v84, 16, v189
	v_and_b32_e32 v85, 0xffff0000, v189
	v_lshlrev_b32_e32 v92, 16, v190
	v_and_b32_e32 v93, 0xffff0000, v190
	v_lshlrev_b32_e32 v86, 16, v191
	v_and_b32_e32 v87, 0xffff0000, v191
	v_pk_fma_f32 v[78:79], v[78:79], v[96:97], v[84:85] op_sel_hi:[1,0,1]
	v_pk_fma_f32 v[76:77], v[76:77], v[96:97], v[90:91] op_sel_hi:[1,0,1]
	v_pk_fma_f32 v[84:85], v[74:75], v[96:97], v[86:87] op_sel_hi:[1,0,1]
	v_pk_fma_f32 v[86:87], v[72:73], v[96:97], v[92:93] op_sel_hi:[1,0,1]
	v_mul_f32_e32 v72, v77, v77
	v_mul_f32_e32 v73, v79, v79
	v_mul_f32_e32 v74, v87, v87
	v_fmac_f32_e32 v72, v76, v76
	v_fmac_f32_e32 v73, v78, v78
	v_mul_f32_e32 v75, v85, v85
	v_fmac_f32_e32 v74, v86, v86
	v_add_f32_e32 v72, v72, v73
	v_add_f32_e32 v72, v74, v72
	v_fmac_f32_e32 v75, v84, v84
	v_add_f32_e32 v72, v75, v72
	v_add_f32_e32 v72, v89, v72
	ds_bpermute_b32 v73, v128, v72
	v_cvt_pk_bf16_f32 v74, v76, v77
	v_cvt_pk_bf16_f32 v75, v78, v79
	v_cvt_pk_bf16_f32 v76, v86, v87
	v_cvt_pk_bf16_f32 v77, v84, v85
	s_waitcnt lgkmcnt(0)
	v_add_f32_e32 v72, v72, v73
	ds_bpermute_b32 v73, v120, v72
	global_store_dwordx4 v[94:95], v[74:77], off offset:256 nt
	s_and_saveexec_b64 s[2:3], vcc
	s_cbranch_execz .LBB0_264
	v_lshl_add_u32 v74, v88, 4, s5
	s_waitcnt lgkmcnt(0)
	v_add_f32_e32 v72, v72, v73
	ds_write_b32 v74, v72
.LBB0_264:
	s_or_b64 exec, exec, s[2:3]
	v_add_u32_e32 v72, 0x80, v144
	v_add_u32_e32 v74, s4, v72
	v_ashrrev_i32_e32 v75, 31, v74
	v_readlane_b32 s2, v252, 36
	v_lshlrev_b64 v[74:75], 12, v[74:75]
	v_readlane_b32 s3, v252, 37
	s_nop 1
	v_lshl_add_u64 v[74:75], s[2:3], 0, v[74:75]
	v_lshl_add_u64 v[78:79], v[2:3], 1, v[74:75]
	s_waitcnt vmcnt(15)
	v_lshlrev_b32_e32 v80, 16, v192
	v_and_b32_e32 v81, 0xffff0000, v192
	v_lshlrev_b32_e32 v74, 16, v193
	v_and_b32_e32 v75, 0xffff0000, v193
	v_lshlrev_b32_e32 v82, 16, v194
	v_and_b32_e32 v83, 0xffff0000, v194
	v_lshlrev_b32_e32 v76, 16, v195
	v_and_b32_e32 v77, 0xffff0000, v195
	v_pk_fma_f32 v[74:75], v[70:71], v[138:139], v[74:75] op_sel_hi:[1,0,1]
	v_pk_fma_f32 v[80:81], v[68:69], v[138:139], v[80:81] op_sel_hi:[1,0,1]
	v_pk_fma_f32 v[76:77], v[66:67], v[138:139], v[76:77] op_sel_hi:[1,0,1]
	v_pk_fma_f32 v[82:83], v[64:65], v[138:139], v[82:83] op_sel_hi:[1,0,1]
	v_cvt_pk_bf16_f32 v64, v80, v81
	v_cvt_pk_bf16_f32 v65, v74, v75
	s_waitcnt lgkmcnt(0)
	v_mul_f32_e32 v73, v81, v81
	v_cvt_pk_bf16_f32 v66, v82, v83
	v_cvt_pk_bf16_f32 v67, v76, v77
	v_mul_f32_e32 v75, v75, v75
	v_mul_f32_e32 v81, v83, v83
	v_fmac_f32_e32 v73, v80, v80
	v_fmac_f32_e32 v75, v74, v74
	v_mul_f32_e32 v77, v77, v77
	v_fmac_f32_e32 v81, v82, v82
	v_add_f32_e32 v73, v73, v75
	v_fmac_f32_e32 v77, v76, v76
	v_add_f32_e32 v73, v81, v73
	v_add_f32_e32 v73, v77, v73
	global_store_dwordx4 v[78:79], v[64:67], off nt
	s_waitcnt vmcnt(15)
	v_lshlrev_b32_e32 v74, 16, v196
	v_and_b32_e32 v75, 0xffff0000, v196
	v_lshlrev_b32_e32 v68, 16, v197
	v_and_b32_e32 v69, 0xffff0000, v197
	v_lshlrev_b32_e32 v76, 16, v198
	v_and_b32_e32 v77, 0xffff0000, v198
	v_lshlrev_b32_e32 v70, 16, v199
	v_and_b32_e32 v71, 0xffff0000, v199
	v_pk_fma_f32 v[62:63], v[62:63], v[138:139], v[68:69] op_sel_hi:[1,0,1]
	v_pk_fma_f32 v[60:61], v[60:61], v[138:139], v[74:75] op_sel_hi:[1,0,1]
	v_pk_fma_f32 v[68:69], v[58:59], v[138:139], v[70:71] op_sel_hi:[1,0,1]
	v_pk_fma_f32 v[70:71], v[56:57], v[138:139], v[76:77] op_sel_hi:[1,0,1]
	v_mul_f32_e32 v56, v61, v61
	v_mul_f32_e32 v57, v63, v63
	v_mul_f32_e32 v58, v71, v71
	v_fmac_f32_e32 v56, v60, v60
	v_fmac_f32_e32 v57, v62, v62
	v_mul_f32_e32 v59, v69, v69
	v_fmac_f32_e32 v58, v70, v70
	v_add_f32_e32 v56, v56, v57
	v_add_f32_e32 v56, v58, v56
	v_fmac_f32_e32 v59, v68, v68
	v_add_f32_e32 v56, v59, v56
	v_add_f32_e32 v56, v73, v56
	ds_bpermute_b32 v57, v128, v56
	v_cvt_pk_bf16_f32 v58, v60, v61
	v_cvt_pk_bf16_f32 v59, v62, v63
	v_cvt_pk_bf16_f32 v60, v70, v71
	v_cvt_pk_bf16_f32 v61, v68, v69
	s_waitcnt lgkmcnt(0)
	v_add_f32_e32 v56, v56, v57
	ds_bpermute_b32 v57, v120, v56
	global_store_dwordx4 v[78:79], v[58:61], off offset:256 nt
	s_and_saveexec_b64 s[2:3], vcc
	s_cbranch_execz .LBB0_266
	v_lshl_add_u32 v58, v72, 4, s5
	s_waitcnt lgkmcnt(0)
	v_add_f32_e32 v56, v56, v57
	ds_write_b32 v58, v56
; #define PG8_LAS __attribute__((address_space(3)))
; __device__ __forceinline__ unsigned cvt_pk_bf16(float lo, float hi) { unsigned r; asm volatile("v_cvt_pk_bf16_f32 %0, %1, %2" : "=v"(r) : "v"(lo), "v"(hi)); return r; }
;     __device__ __forceinline__ void khook(f32x4 (&acc)[2][2][4][2], int hb, int wr, int fr, PG8_LAS unsigned char* lds) const {
;     ...
;             for (int m = 0; m < 4; ++m) { const float r = RT[ai * HALF + m * 16];
; #pragma unroll
;                 for (int bj = 0; bj < 2; ++bj)
; #pragma unroll
;                     for (int n = 0; n < 2; ++n) acc[ai][bj][m][n] = acc[ai][bj][m][n] * r; } }
;     __device__ __forceinline__ void fused(f32x4 (&acc)[2][2][4][2], const Unit& u, int wr, int wc, int fr, int fq, PG8_LAS unsigned char* lds, int wid, int lane) const {
;         khook(acc, 0, wr, fr, lds);
;         PG8_LAS float* P = (PG8_LAS float*)lds;
;         const int col0 = u.pn * BM + wc * 32 + 8 * fq;
; #pragma unroll
;         for (int ai = 0; ai < 2; ++ai)
; #pragma unroll
;             for (int m = 0; m < 4; ++m) { const int rl = ai * HALF + wr * 64 + m * 16 + fr; const size_t off = (size_t)(u.pm * BM + rl) * ldc + col0; float q = 0.f;
; #pragma unroll
;                 for (int bj = 0; bj < 2; ++bj) { const u32x4 hb = *(const u32x4*)(xb + off + bj * HALF);
;                     const f32x4 b0 = (f32x4){__uint_as_float(hb.x << 16), __uint_as_float(hb.x & 0xffff0000u), __uint_as_float(hb.y << 16), __uint_as_float(hb.y & 0xffff0000u)};
;                     const f32x4 b1 = (f32x4){__uint_as_float(hb.z << 16), __uint_as_float(hb.z & 0xffff0000u), __uint_as_float(hb.w << 16), __uint_as_float(hb.w & 0xffff0000u)};
;                     const f32x4 v0 = b0 + acc[ai][bj][m][0], v1 = b1 + acc[ai][bj][m][1];
;                     u32x4 w; w.x = cvt_pk_bf16(v0[0], v0[1]); w.y = cvt_pk_bf16(v0[2], v0[3]); w.z = cvt_pk_bf16(v1[0], v1[1]); w.w = cvt_pk_bf16(v1[2], v1[3]);
;                     *(u32x4*)(xb + off + bj * HALF) = w;
;                     q += (v0[0] * v0[0] + v0[1] * v0[1]) + (v0[2] * v0[2] + v0[3] * v0[3]) + (v1[0] * v1[0] + v1[1] * v1[1]) + (v1[2] * v1[2] + v1[3] * v1[3]); }
;                 q += __shfl_xor(q, 16); q += __shfl_xor(q, 32);
;                 if (fq == 0) P[rl * 4 + wc] = q; }
.LBB0_266:
	s_or_b64 exec, exec, s[2:3]
	v_add_u32_e32 v56, 0x90, v144
	v_add_u32_e32 v58, s4, v56
	v_ashrrev_i32_e32 v59, 31, v58
	v_readlane_b32 s2, v252, 36
	v_lshlrev_b64 v[58:59], 12, v[58:59]
	v_readlane_b32 s3, v252, 37
	v_mov_b32_e32 v64, v139
	s_nop 0
	v_lshl_add_u64 v[58:59], s[2:3], 0, v[58:59]
	v_lshl_add_u64 v[62:63], v[2:3], 1, v[58:59]
	s_waitcnt vmcnt(15)
	v_lshlrev_b32_e32 v66, 16, v200
	v_and_b32_e32 v67, 0xffff0000, v200
	v_lshlrev_b32_e32 v58, 16, v201
	v_and_b32_e32 v59, 0xffff0000, v201
	v_lshlrev_b32_e32 v68, 16, v202
	v_and_b32_e32 v69, 0xffff0000, v202
	v_lshlrev_b32_e32 v60, 16, v203
	v_and_b32_e32 v61, 0xffff0000, v203
	v_pk_fma_f32 v[58:59], v[54:55], v[64:65], v[58:59] op_sel_hi:[1,0,1]
	v_pk_fma_f32 v[66:67], v[52:53], v[64:65], v[66:67] op_sel_hi:[1,0,1]
	v_pk_fma_f32 v[60:61], v[50:51], v[64:65], v[60:61] op_sel_hi:[1,0,1]
	v_pk_fma_f32 v[68:69], v[48:49], v[64:65], v[68:69] op_sel_hi:[1,0,1]
	v_cvt_pk_bf16_f32 v48, v66, v67
	v_cvt_pk_bf16_f32 v49, v58, v59
	s_waitcnt lgkmcnt(0)
	v_mul_f32_e32 v57, v67, v67
	v_cvt_pk_bf16_f32 v50, v68, v69
	v_cvt_pk_bf16_f32 v51, v60, v61
	v_mul_f32_e32 v59, v59, v59
	v_mul_f32_e32 v65, v69, v69
	v_fmac_f32_e32 v57, v66, v66
	v_fmac_f32_e32 v59, v58, v58
	v_mul_f32_e32 v61, v61, v61
	v_fmac_f32_e32 v65, v68, v68
	v_add_f32_e32 v57, v57, v59
	v_fmac_f32_e32 v61, v60, v60
	v_add_f32_e32 v57, v65, v57
	v_add_f32_e32 v57, v61, v57
	global_store_dwordx4 v[62:63], v[48:51], off nt
	s_waitcnt vmcnt(15)
	v_lshlrev_b32_e32 v58, 16, v204
	v_and_b32_e32 v59, 0xffff0000, v204
	v_lshlrev_b32_e32 v52, 16, v205
	v_and_b32_e32 v53, 0xffff0000, v205
	v_lshlrev_b32_e32 v60, 16, v206
	v_and_b32_e32 v61, 0xffff0000, v206
	v_lshlrev_b32_e32 v54, 16, v207
	v_and_b32_e32 v55, 0xffff0000, v207
	v_pk_fma_f32 v[46:47], v[46:47], v[64:65], v[52:53] op_sel_hi:[1,0,1]
	v_pk_fma_f32 v[44:45], v[44:45], v[64:65], v[58:59] op_sel_hi:[1,0,1]
	v_pk_fma_f32 v[52:53], v[42:43], v[64:65], v[54:55] op_sel_hi:[1,0,1]
	v_pk_fma_f32 v[54:55], v[40:41], v[64:65], v[60:61] op_sel_hi:[1,0,1]
	v_mul_f32_e32 v40, v45, v45
	v_mul_f32_e32 v41, v47, v47
	v_mul_f32_e32 v42, v55, v55
	v_fmac_f32_e32 v40, v44, v44
	v_fmac_f32_e32 v41, v46, v46
	v_mul_f32_e32 v43, v53, v53
	v_fmac_f32_e32 v42, v54, v54
	v_add_f32_e32 v40, v40, v41
	v_add_f32_e32 v40, v42, v40
	v_fmac_f32_e32 v43, v52, v52
	v_add_f32_e32 v40, v43, v40
	v_add_f32_e32 v40, v57, v40
	ds_bpermute_b32 v41, v128, v40
	v_cvt_pk_bf16_f32 v42, v44, v45
	v_cvt_pk_bf16_f32 v43, v46, v47
	v_cvt_pk_bf16_f32 v44, v54, v55
	v_cvt_pk_bf16_f32 v45, v52, v53
	s_waitcnt lgkmcnt(0)
	v_add_f32_e32 v40, v40, v41
	ds_bpermute_b32 v41, v120, v40
	global_store_dwordx4 v[62:63], v[42:45], off offset:256 nt
	s_and_saveexec_b64 s[2:3], vcc
	s_cbranch_execz .LBB0_268
	v_lshl_add_u32 v42, v56, 4, s5
	s_waitcnt lgkmcnt(0)
	v_add_f32_e32 v40, v40, v41
	ds_write_b32 v42, v40
; #define PG8_LAS __attribute__((address_space(3)))
; __device__ __forceinline__ unsigned cvt_pk_bf16(float lo, float hi) { unsigned r; asm volatile("v_cvt_pk_bf16_f32 %0, %1, %2" : "=v"(r) : "v"(lo), "v"(hi)); return r; }
;     __device__ __forceinline__ void khook(f32x4 (&acc)[2][2][4][2], int hb, int wr, int fr, PG8_LAS unsigned char* lds) const {
;     ...
;             for (int m = 0; m < 4; ++m) { const float r = RT[ai * HALF + m * 16];
; #pragma unroll
;                 for (int bj = 0; bj < 2; ++bj)
; #pragma unroll
;                     for (int n = 0; n < 2; ++n) acc[ai][bj][m][n] = acc[ai][bj][m][n] * r; } }
;     __device__ __forceinline__ void fused(f32x4 (&acc)[2][2][4][2], const Unit& u, int wr, int wc, int fr, int fq, PG8_LAS unsigned char* lds, int wid, int lane) const {
;         khook(acc, 0, wr, fr, lds);
;         PG8_LAS float* P = (PG8_LAS float*)lds;
;         const int col0 = u.pn * BM + wc * 32 + 8 * fq;
; #pragma unroll
;         for (int ai = 0; ai < 2; ++ai)
; #pragma unroll
;             for (int m = 0; m < 4; ++m) { const int rl = ai * HALF + wr * 64 + m * 16 + fr; const size_t off = (size_t)(u.pm * BM + rl) * ldc + col0; float q = 0.f;
; #pragma unroll
;                 for (int bj = 0; bj < 2; ++bj) { const u32x4 hb = *(const u32x4*)(xb + off + bj * HALF);
;                     const f32x4 b0 = (f32x4){__uint_as_float(hb.x << 16), __uint_as_float(hb.x & 0xffff0000u), __uint_as_float(hb.y << 16), __uint_as_float(hb.y & 0xffff0000u)};
;                     const f32x4 b1 = (f32x4){__uint_as_float(hb.z << 16), __uint_as_float(hb.z & 0xffff0000u), __uint_as_float(hb.w << 16), __uint_as_float(hb.w & 0xffff0000u)};
;                     const f32x4 v0 = b0 + acc[ai][bj][m][0], v1 = b1 + acc[ai][bj][m][1];
;                     u32x4 w; w.x = cvt_pk_bf16(v0[0], v0[1]); w.y = cvt_pk_bf16(v0[2], v0[3]); w.z = cvt_pk_bf16(v1[0], v1[1]); w.w = cvt_pk_bf16(v1[2], v1[3]);
;                     *(u32x4*)(xb + off + bj * HALF) = w;
;                     q += (v0[0] * v0[0] + v0[1] * v0[1]) + (v0[2] * v0[2] + v0[3] * v0[3]) + (v1[0] * v1[0] + v1[1] * v1[1]) + (v1[2] * v1[2] + v1[3] * v1[3]); }
;                 q += __shfl_xor(q, 16); q += __shfl_xor(q, 32);
;                 if (fq == 0) P[rl * 4 + wc] = q; }
.LBB0_268:
	s_or_b64 exec, exec, s[2:3]
	v_add_u32_e32 v40, 0xa0, v144
	v_add_u32_e32 v42, s4, v40
	v_ashrrev_i32_e32 v43, 31, v42
	v_readlane_b32 s2, v252, 36
	v_lshlrev_b64 v[42:43], 12, v[42:43]
	v_readlane_b32 s3, v252, 37
	s_nop 1
	v_lshl_add_u64 v[42:43], s[2:3], 0, v[42:43]
	v_lshl_add_u64 v[46:47], v[2:3], 1, v[42:43]
	s_waitcnt vmcnt(15)
	v_lshlrev_b32_e32 v48, 16, v224
	v_and_b32_e32 v49, 0xffff0000, v224
	v_lshlrev_b32_e32 v42, 16, v225
	v_and_b32_e32 v43, 0xffff0000, v225
	v_lshlrev_b32_e32 v50, 16, v226
	v_and_b32_e32 v51, 0xffff0000, v226
	v_lshlrev_b32_e32 v44, 16, v227
	v_and_b32_e32 v45, 0xffff0000, v227
	v_pk_fma_f32 v[42:43], v[38:39], v[136:137], v[42:43] op_sel_hi:[1,0,1]
	v_pk_fma_f32 v[48:49], v[36:37], v[136:137], v[48:49] op_sel_hi:[1,0,1]
	v_pk_fma_f32 v[44:45], v[34:35], v[136:137], v[44:45] op_sel_hi:[1,0,1]
	v_pk_fma_f32 v[50:51], v[32:33], v[136:137], v[50:51] op_sel_hi:[1,0,1]
	v_cvt_pk_bf16_f32 v32, v48, v49
	v_cvt_pk_bf16_f32 v33, v42, v43
	s_waitcnt lgkmcnt(0)
	v_mul_f32_e32 v41, v49, v49
	v_cvt_pk_bf16_f32 v34, v50, v51
	v_cvt_pk_bf16_f32 v35, v44, v45
	v_mul_f32_e32 v43, v43, v43
	v_mul_f32_e32 v49, v51, v51
	v_fmac_f32_e32 v41, v48, v48
	v_fmac_f32_e32 v43, v42, v42
	v_mul_f32_e32 v45, v45, v45
	v_fmac_f32_e32 v49, v50, v50
	v_add_f32_e32 v41, v41, v43
	v_fmac_f32_e32 v45, v44, v44
	v_add_f32_e32 v41, v49, v41
	v_add_f32_e32 v41, v45, v41
	global_store_dwordx4 v[46:47], v[32:35], off nt
	s_waitcnt vmcnt(15)
	v_lshlrev_b32_e32 v42, 16, v228
	v_and_b32_e32 v43, 0xffff0000, v228
	v_lshlrev_b32_e32 v36, 16, v229
	v_and_b32_e32 v37, 0xffff0000, v229
	v_lshlrev_b32_e32 v44, 16, v230
	v_and_b32_e32 v45, 0xffff0000, v230
	v_lshlrev_b32_e32 v38, 16, v231
	v_and_b32_e32 v39, 0xffff0000, v231
	v_pk_fma_f32 v[30:31], v[30:31], v[136:137], v[36:37] op_sel_hi:[1,0,1]
	v_pk_fma_f32 v[28:29], v[28:29], v[136:137], v[42:43] op_sel_hi:[1,0,1]
	v_pk_fma_f32 v[36:37], v[26:27], v[136:137], v[38:39] op_sel_hi:[1,0,1]
	v_pk_fma_f32 v[38:39], v[24:25], v[136:137], v[44:45] op_sel_hi:[1,0,1]
	v_mul_f32_e32 v24, v29, v29
	v_mul_f32_e32 v25, v31, v31
	v_mul_f32_e32 v26, v39, v39
	v_fmac_f32_e32 v24, v28, v28
	v_fmac_f32_e32 v25, v30, v30
	v_mul_f32_e32 v27, v37, v37
	v_fmac_f32_e32 v26, v38, v38
	v_add_f32_e32 v24, v24, v25
	v_add_f32_e32 v24, v26, v24
	v_fmac_f32_e32 v27, v36, v36
	v_add_f32_e32 v24, v27, v24
	v_add_f32_e32 v24, v41, v24
	ds_bpermute_b32 v25, v128, v24
	v_cvt_pk_bf16_f32 v26, v28, v29
	v_cvt_pk_bf16_f32 v27, v30, v31
	v_cvt_pk_bf16_f32 v28, v38, v39
	v_cvt_pk_bf16_f32 v29, v36, v37
	s_waitcnt lgkmcnt(0)
	v_add_f32_e32 v24, v24, v25
	ds_bpermute_b32 v25, v120, v24
	global_store_dwordx4 v[46:47], v[26:29], off offset:256 nt
	s_and_saveexec_b64 s[2:3], vcc
	s_cbranch_execz .LBB0_270
	v_lshl_add_u32 v26, v40, 4, s5
	s_waitcnt lgkmcnt(0)
	v_add_f32_e32 v24, v24, v25
	ds_write_b32 v26, v24
.LBB0_270:
	s_or_b64 exec, exec, s[2:3]
	v_add_u32_e32 v24, 0xb0, v144
	v_add_u32_e32 v26, s4, v24
	v_ashrrev_i32_e32 v27, 31, v26
	v_readlane_b32 s2, v252, 36
	v_lshlrev_b64 v[26:27], 12, v[26:27]
	v_readlane_b32 s3, v252, 37
	s_nop 1
	v_lshl_add_u64 v[26:27], s[2:3], 0, v[26:27]
	v_lshl_add_u64 v[30:31], v[2:3], 1, v[26:27]
	v_mov_b32_e32 v2, v137
	s_waitcnt vmcnt(15)
	v_lshlrev_b32_e32 v32, 16, v232
	v_and_b32_e32 v33, 0xffff0000, v232
	v_lshlrev_b32_e32 v26, 16, v233
	v_and_b32_e32 v27, 0xffff0000, v233
	v_lshlrev_b32_e32 v34, 16, v234
	v_and_b32_e32 v35, 0xffff0000, v234
	v_lshlrev_b32_e32 v28, 16, v235
	v_and_b32_e32 v29, 0xffff0000, v235
	v_pk_fma_f32 v[26:27], v[22:23], v[2:3], v[26:27] op_sel_hi:[1,0,1]
	v_pk_fma_f32 v[32:33], v[20:21], v[2:3], v[32:33] op_sel_hi:[1,0,1]
	v_pk_fma_f32 v[28:29], v[18:19], v[2:3], v[28:29] op_sel_hi:[1,0,1]
	v_pk_fma_f32 v[34:35], v[16:17], v[2:3], v[34:35] op_sel_hi:[1,0,1]
	v_cvt_pk_bf16_f32 v16, v32, v33
	v_cvt_pk_bf16_f32 v17, v26, v27
	v_mul_f32_e32 v3, v33, v33
	v_cvt_pk_bf16_f32 v18, v34, v35
	v_cvt_pk_bf16_f32 v19, v28, v29
	s_waitcnt lgkmcnt(0)
	v_mul_f32_e32 v25, v27, v27
	v_mul_f32_e32 v27, v35, v35
	v_fmac_f32_e32 v3, v32, v32
	v_fmac_f32_e32 v25, v26, v26
	v_mul_f32_e32 v29, v29, v29
	v_fmac_f32_e32 v27, v34, v34
	v_add_f32_e32 v3, v3, v25
	v_fmac_f32_e32 v29, v28, v28
	v_add_f32_e32 v3, v27, v3
	v_add_f32_e32 v3, v29, v3
	global_store_dwordx4 v[30:31], v[16:19], off nt
	s_waitcnt vmcnt(15)
	v_lshlrev_b32_e32 v26, 16, v236
	v_and_b32_e32 v27, 0xffff0000, v236
	v_lshlrev_b32_e32 v20, 16, v237
	v_and_b32_e32 v21, 0xffff0000, v237
	v_lshlrev_b32_e32 v28, 16, v238
	v_and_b32_e32 v29, 0xffff0000, v238
	v_lshlrev_b32_e32 v22, 16, v239
	v_and_b32_e32 v23, 0xffff0000, v239
	v_pk_fma_f32 v[14:15], v[14:15], v[2:3], v[20:21] op_sel_hi:[1,0,1]
	v_pk_fma_f32 v[12:13], v[12:13], v[2:3], v[26:27] op_sel_hi:[1,0,1]
	v_pk_fma_f32 v[20:21], v[10:11], v[2:3], v[22:23] op_sel_hi:[1,0,1]
	v_pk_fma_f32 v[10:11], v[8:9], v[2:3], v[28:29] op_sel_hi:[1,0,1]
	v_mul_f32_e32 v2, v13, v13
	v_mul_f32_e32 v8, v15, v15
	v_mul_f32_e32 v9, v11, v11
	v_fmac_f32_e32 v2, v12, v12
	v_fmac_f32_e32 v8, v14, v14
	v_mul_f32_e32 v22, v21, v21
	v_fmac_f32_e32 v9, v10, v10
	v_add_f32_e32 v2, v2, v8
	v_add_f32_e32 v2, v9, v2
	v_fmac_f32_e32 v22, v20, v20
	v_add_f32_e32 v2, v22, v2
	v_add_f32_e32 v2, v3, v2
	ds_bpermute_b32 v3, v128, v2
	v_cvt_pk_bf16_f32 v8, v12, v13
	v_cvt_pk_bf16_f32 v9, v14, v15
	v_cvt_pk_bf16_f32 v10, v10, v11
	v_cvt_pk_bf16_f32 v11, v20, v21
	s_waitcnt lgkmcnt(0)
	v_add_f32_e32 v2, v2, v3
	ds_bpermute_b32 v3, v120, v2
	global_store_dwordx4 v[30:31], v[8:11], off offset:256 nt
	s_and_saveexec_b64 s[2:3], vcc
	s_cbranch_execz .LBB0_272
	v_lshl_add_u32 v8, v24, 4, s5
	s_waitcnt lgkmcnt(0)
	v_add_f32_e32 v2, v2, v3
	ds_write_b32 v8, v2

; #define PG8_WAIT_V(n) asm volatile("s_waitcnt vmcnt(" #n ")" ::: "memory")
; #define PG8_BAR __builtin_amdgcn_s_barrier()
;     __device__ __forceinline__ void fused(f32x4 (&acc)[2][2][4][2], const Unit& u, int wr, int wc, int fr, int fq, PG8_LAS unsigned char* lds, int wid, int lane) const {
;     ...
;             for (int m = 0; m < 4; ++m) { const int rl = ai * HALF + wr * 64 + m * 16 + fr; const size_t off = (size_t)(u.pm * BM + rl) * ldc + col0; float q = 0.f;
; #pragma unroll
;                 for (int bj = 0; bj < 2; ++bj) { const u32x4 hb = *(const u32x4*)(xb + off + bj * HALF);
; template <class Epi, class Sched, bool ALIGN_EPI = false, bool SP2 = false>
; __device__ __forceinline__ void gemm_phase(PG8_LAS unsigned char* lds, const Gemm g, const Sched& S, const Epi& E) {
;     ...
;     PG8_WAIT_V(0);
;     if constexpr (!ALIGN_EPI) { if (wr == 0) PG8_BAR; }
;     PG8_BAR;
;     if constexpr (Epi::AFTER_DRAIN) { E.fused(acc, cur, wr, wc, fr, fq, lds, wid, lane); S.done(cur); }
.LBB0_297:
	s_lshl_b32 s2, s72, 5
	s_lshl_b32 s3, s12, 8
	s_or_b32 s2, s3, s2
	s_lshl_b32 s3, s42, 8
	v_lshrrev_b32_e32 v208, 1, v150
	v_and_or_b32 v208, v208, 24, s2
	v_add_u32_e32 v209, s3, v149
	v_lshlrev_b32_e32 v209, 12, v209
	v_lshl_add_u32 v209, v208, 1, v209
	v_readlane_b32 s2, v252, 36
	v_readlane_b32 s3, v252, 37
	s_nop 4
	global_load_dwordx4 v[156:159], v209, s[2:3] nt
	global_load_dwordx4 v[160:163], v209, s[2:3] offset:256 nt
	v_add_u32_e32 v209, 0x10000, v209
	global_load_dwordx4 v[164:167], v209, s[2:3] nt
	global_load_dwordx4 v[168:171], v209, s[2:3] offset:256 nt
	v_add_u32_e32 v209, 0x10000, v209
	global_load_dwordx4 v[172:175], v209, s[2:3] nt
	global_load_dwordx4 v[176:179], v209, s[2:3] offset:256 nt
	v_add_u32_e32 v209, 0x10000, v209
	global_load_dwordx4 v[184:187], v209, s[2:3] nt
	global_load_dwordx4 v[188:191], v209, s[2:3] offset:256 nt
	v_add_u32_e32 v209, 0x50000, v209
	global_load_dwordx4 v[192:195], v209, s[2:3] nt
	global_load_dwordx4 v[196:199], v209, s[2:3] offset:256 nt
	v_add_u32_e32 v209, 0x10000, v209
	global_load_dwordx4 v[200:203], v209, s[2:3] nt
	global_load_dwordx4 v[204:207], v209, s[2:3] offset:256 nt
	v_add_u32_e32 v209, 0x10000, v209
	global_load_dwordx4 v[224:227], v209, s[2:3] nt
	global_load_dwordx4 v[228:231], v209, s[2:3] offset:256 nt
	v_add_u32_e32 v209, 0x10000, v209
	global_load_dwordx4 v[232:235], v209, s[2:3] nt
	global_load_dwordx4 v[236:239], v209, s[2:3] offset:256 nt
	s_waitcnt vmcnt(16)
	s_cmpk_lt_u32 s13, 0x100
	s_cselect_b64 s[6:7], -1, 0
	s_cmpk_gt_u32 s13, 0xff
	s_cbranch_scc1 .LBB0_299
	s_barrier
